# nt hint also on the stores of the out-proj residual epilogues (phases 5, 11) and the final norm output
# baseline (speedup 1.0000x reference)
; #define PG8_STAGE(bufoff, gbase, voff) do { _Pragma("unroll") for (int _i = 0; _i < 2; ++_i) \
;         __builtin_amdgcn_global_load_lds((const unsigned*)((const char*)(gbase) + (voff)[_i]), (LAS unsigned*)(lds + (bufoff) + ldsw + _i * 8192), 16, 0, 0); } while (0)
; #define PG8_LDA(dst, b, h) do { _Pragma("unroll") for (int m = 0; m < 4; ++m) _Pragma("unroll") for (int k = 0; k < 2; ++k) dst[m][k] = *(const LAS bf16x8*)(lds + PG8_SA(b, h) + aoff + m * 2048 + k * 1024); } while (0)
; #define PG8_LDB(dst, b, h) do { _Pragma("unroll") for (int n = 0; n < 2; ++n) _Pragma("unroll") for (int k = 0; k < 2; ++k) dst[n][k] = *(const LAS bf16x8*)(lds + PG8_SB(b, h) + boff + n * 2048 + k * 1024); } while (0)
; #define PG8_MMA(ai, bj, At, Bt) do { __builtin_amdgcn_s_setprio(1); _Pragma("unroll") for (int m = 0; m < 4; ++m) _Pragma("unroll") for (int n = 0; n < 2; ++n) _Pragma("unroll") for (int k = 0; k < 2; ++k) \
;         acc[ai][bj][m][n] = __builtin_amdgcn_mfma_f32_16x16x32_bf16(Bt[n][k], At[m][k], acc[ai][bj][m][n], 0, 0, 0); __builtin_amdgcn_s_setprio(0); } while (0)
; #define PG8_WAIT_L(n) asm volatile("s_waitcnt lgkmcnt(" #n ")" ::: "memory")
; #define PG8_BAR __builtin_amdgcn_s_barrier()
; #define PG8_SCHED __builtin_amdgcn_sched_barrier(0)
; template <class Epi, class Sched>
; DI void gemm_phase(LAS unsigned char* lds, const Gemm g, const Sched& S, const Epi& E) {
;     ...
;             PG8_LDB(B0, 0, 0); PG8_SCHED; PG8_LDA(At, 0, 0); PG8_STAGE(PG8_SA(1, 1), a1 + hstep, voffA);
;             PG8_WAIT_L(8); PG8_BAR; PG8_WAIT_L(0); PG8_MMA(0, 0, At, B0); PG8_BAR; PG8_SCHED;
;             PG8_LDB(B1, 0, 1); PG8_STAGE(PG8_SB(0, 0), b2, voffB);
;             PG8_BAR; PG8_WAIT_L(0); PG8_MMA(0, 1, At, B1); PG8_BAR;
;             PG8_LDA(At, 0, 1); PG8_STAGE(PG8_SA(0, 0), a2, voffA);
;             PG8_BAR; PG8_WAIT_L(0); PG8_MMA(1, 0, At, B0); PG8_BAR; PG8_SCHED;
.LBB0_1007:
	ds_read_b128 v[140:143], v147
	ds_read_b128 v[154:157], v147 offset:1024
	ds_read_b128 v[158:161], v147 offset:2048
	ds_read_b128 v[164:167], v147 offset:3072
	s_add_u32 s24, s22, 0xfffc0080
	s_addc_u32 s25, s23, -1
	s_cmp_eq_u32 s66, 12
	s_cselect_b32 s27, s47, s25
	s_cselect_b32 s26, s53, s24
	s_cselect_b32 s25, s54, s59
	s_cselect_b32 s24, s55, s58
	s_mov_b32 m0, s36
	v_lshl_add_u64 v[150:151], s[22:23], 0, v[136:137]
	ds_read_b128 v[168:171], v148
	ds_read_b128 v[172:175], v148 offset:1024
	ds_read_b128 v[176:179], v148 offset:2048
	ds_read_b128 v[180:183], v148 offset:3072
	ds_read_b128 v[184:187], v148 offset:4096
	ds_read_b128 v[188:191], v148 offset:5120
	ds_read_b128 v[192:195], v148 offset:6144
	ds_read_b128 v[198:201], v148 offset:7168
	global_load_lds_dwordx4 v[150:151], off
	v_lshl_add_u64 v[150:151], s[22:23], 0, v[138:139]
	s_mov_b32 m0, s37
	s_nop 0
	global_load_lds_dwordx4 v[150:151], off
	s_waitcnt lgkmcnt(8)
	s_barrier
	s_waitcnt lgkmcnt(0)
	s_setprio 1
	s_waitcnt lgkmcnt(0)
	v_mfma_f32_16x16x32_bf16 v[126:129], v[140:143], v[168:171], v[126:129]
	v_mfma_f32_16x16x32_bf16 v[122:125], v[158:161], v[168:171], v[122:125]
	v_mfma_f32_16x16x32_bf16 v[114:117], v[140:143], v[176:179], v[114:117]
	v_mfma_f32_16x16x32_bf16 v[106:109], v[158:161], v[176:179], v[106:109]
	v_mfma_f32_16x16x32_bf16 v[98:101], v[140:143], v[184:187], v[98:101]
	v_mfma_f32_16x16x32_bf16 v[90:93], v[158:161], v[184:187], v[90:93]
	v_mfma_f32_16x16x32_bf16 v[82:85], v[140:143], v[192:195], v[82:85]
	v_mfma_f32_16x16x32_bf16 v[74:77], v[158:161], v[192:195], v[74:77]
	v_mfma_f32_16x16x32_bf16 v[126:129], v[154:157], v[172:175], v[126:129]
	v_mfma_f32_16x16x32_bf16 v[122:125], v[164:167], v[172:175], v[122:125]
	v_mfma_f32_16x16x32_bf16 v[114:117], v[154:157], v[180:183], v[114:117]
	v_mfma_f32_16x16x32_bf16 v[106:109], v[164:167], v[180:183], v[106:109]
	v_mfma_f32_16x16x32_bf16 v[98:101], v[154:157], v[188:191], v[98:101]
	v_mfma_f32_16x16x32_bf16 v[90:93], v[164:167], v[188:191], v[90:93]
	v_mfma_f32_16x16x32_bf16 v[82:85], v[154:157], v[198:201], v[82:85]
	v_mfma_f32_16x16x32_bf16 v[74:77], v[164:167], v[198:201], v[74:77]
	s_setprio 0
	s_barrier
	s_mov_b32 m0, s38
	v_lshl_add_u64 v[150:151], s[24:25], 0, v[132:133]
	ds_read_b128 v[202:205], v149
	ds_read_b128 v[206:209], v149 offset:1024
	ds_read_b128 v[210:213], v149 offset:2048
	ds_read_b128 v[214:217], v149 offset:3072
	global_load_lds_dwordx4 v[150:151], off
	v_lshl_add_u64 v[218:219], s[24:25], 0, v[130:131]
	s_mov_b32 m0, s39
	s_nop 0
	global_load_lds_dwordx4 v[218:219], off
	s_barrier
	s_waitcnt lgkmcnt(0)
	s_setprio 1
	s_waitcnt lgkmcnt(0)
	v_mfma_f32_16x16x32_bf16 v[118:121], v[202:205], v[168:171], v[118:121]
	v_mfma_f32_16x16x32_bf16 v[110:113], v[210:213], v[168:171], v[110:113]
	v_mfma_f32_16x16x32_bf16 v[102:105], v[202:205], v[176:179], v[102:105]
	v_mfma_f32_16x16x32_bf16 v[94:97], v[210:213], v[176:179], v[94:97]
	v_mfma_f32_16x16x32_bf16 v[86:89], v[202:205], v[184:187], v[86:89]
	v_mfma_f32_16x16x32_bf16 v[78:81], v[210:213], v[184:187], v[78:81]
	v_mfma_f32_16x16x32_bf16 v[70:73], v[202:205], v[192:195], v[70:73]
	v_mfma_f32_16x16x32_bf16 v[66:69], v[210:213], v[192:195], v[66:69]
	v_mfma_f32_16x16x32_bf16 v[118:121], v[206:209], v[172:175], v[118:121]
	v_mfma_f32_16x16x32_bf16 v[110:113], v[214:217], v[172:175], v[110:113]
	v_mfma_f32_16x16x32_bf16 v[102:105], v[206:209], v[180:183], v[102:105]
	v_mfma_f32_16x16x32_bf16 v[94:97], v[214:217], v[180:183], v[94:97]
	v_mfma_f32_16x16x32_bf16 v[86:89], v[206:209], v[188:191], v[86:89]
	v_mfma_f32_16x16x32_bf16 v[78:81], v[214:217], v[188:191], v[78:81]
	v_mfma_f32_16x16x32_bf16 v[70:73], v[206:209], v[198:201], v[70:73]
	v_mfma_f32_16x16x32_bf16 v[66:69], v[214:217], v[198:201], v[66:69]
	s_setprio 0
	s_mov_b32 m0, s13
	v_lshl_add_u64 v[220:221], s[26:27], 0, v[132:133]
	s_barrier
	ds_read_b128 v[168:171], v148 offset:16384
	ds_read_b128 v[172:175], v148 offset:17408
	ds_read_b128 v[176:179], v148 offset:18432
	ds_read_b128 v[180:183], v148 offset:19456
	ds_read_b128 v[184:187], v148 offset:20480
	ds_read_b128 v[188:191], v148 offset:21504
	ds_read_b128 v[192:195], v148 offset:22528
	ds_read_b128 v[198:201], v148 offset:23552
	global_load_lds_dwordx4 v[220:221], off
	v_lshl_add_u64 v[222:223], s[26:27], 0, v[130:131]
	s_mov_b32 m0, s28
	s_nop 0
	global_load_lds_dwordx4 v[222:223], off
	s_barrier
	s_waitcnt lgkmcnt(0)
	s_setprio 1
	s_waitcnt lgkmcnt(0)
	v_mfma_f32_16x16x32_bf16 v[62:65], v[140:143], v[168:171], v[62:65]
	v_mfma_f32_16x16x32_bf16 v[58:61], v[158:161], v[168:171], v[58:61]
	v_mfma_f32_16x16x32_bf16 v[50:53], v[140:143], v[176:179], v[50:53]
	v_mfma_f32_16x16x32_bf16 v[42:45], v[158:161], v[176:179], v[42:45]
	v_mfma_f32_16x16x32_bf16 v[34:37], v[140:143], v[184:187], v[34:37]
	v_mfma_f32_16x16x32_bf16 v[26:29], v[158:161], v[184:187], v[26:29]
	v_mfma_f32_16x16x32_bf16 v[18:21], v[140:143], v[192:195], v[18:21]
	v_mfma_f32_16x16x32_bf16 v[10:13], v[158:161], v[192:195], v[10:13]
	v_mfma_f32_16x16x32_bf16 v[62:65], v[154:157], v[172:175], v[62:65]
	v_mfma_f32_16x16x32_bf16 v[58:61], v[164:167], v[172:175], v[58:61]
	v_mfma_f32_16x16x32_bf16 v[50:53], v[154:157], v[180:183], v[50:53]
	v_mfma_f32_16x16x32_bf16 v[42:45], v[164:167], v[180:183], v[42:45]
	v_mfma_f32_16x16x32_bf16 v[34:37], v[154:157], v[188:191], v[34:37]
	v_mfma_f32_16x16x32_bf16 v[26:29], v[164:167], v[188:191], v[26:29]
	v_mfma_f32_16x16x32_bf16 v[18:21], v[154:157], v[198:201], v[18:21]
	v_mfma_f32_16x16x32_bf16 v[10:13], v[164:167], v[198:201], v[10:13]
	s_setprio 0
	s_barrier
; #define PG8_STAGE(bufoff, gbase, voff) do { _Pragma("unroll") for (int _i = 0; _i < 2; ++_i) \
;         __builtin_amdgcn_global_load_lds((const unsigned*)((const char*)(gbase) + (voff)[_i]), (LAS unsigned*)(lds + (bufoff) + ldsw + _i * 8192), 16, 0, 0); } while (0)
; #define PG8_LDA(dst, b, h) do { _Pragma("unroll") for (int m = 0; m < 4; ++m) _Pragma("unroll") for (int k = 0; k < 2; ++k) dst[m][k] = *(const LAS bf16x8*)(lds + PG8_SA(b, h) + aoff + m * 2048 + k * 1024); } while (0)
; #define PG8_LDB(dst, b, h) do { _Pragma("unroll") for (int n = 0; n < 2; ++n) _Pragma("unroll") for (int k = 0; k < 2; ++k) dst[n][k] = *(const LAS bf16x8*)(lds + PG8_SB(b, h) + boff + n * 2048 + k * 1024); } while (0)
; #define PG8_MMA(ai, bj, At, Bt) do { __builtin_amdgcn_s_setprio(1); _Pragma("unroll") for (int m = 0; m < 4; ++m) _Pragma("unroll") for (int n = 0; n < 2; ++n) _Pragma("unroll") for (int k = 0; k < 2; ++k) \
;         acc[ai][bj][m][n] = __builtin_amdgcn_mfma_f32_16x16x32_bf16(Bt[n][k], At[m][k], acc[ai][bj][m][n], 0, 0, 0); __builtin_amdgcn_s_setprio(0); } while (0)
; #define PG8_WAIT_V(n) asm volatile("s_waitcnt vmcnt(" #n ")" ::: "memory")
; #define PG8_WAIT_L(n) asm volatile("s_waitcnt lgkmcnt(" #n ")" ::: "memory")
; #define PG8_BAR __builtin_amdgcn_s_barrier()
; #define PG8_SCHED __builtin_amdgcn_sched_barrier(0)
; template <class Epi, class Sched>
; DI void gemm_phase(LAS unsigned char* lds, const Gemm g, const Sched& S, const Epi& E) {
;     ...
;             PG8_BAR; PG8_WAIT_L(0); PG8_MMA(1, 0, At, B0); PG8_BAR; PG8_SCHED;
;             PG8_STAGE(PG8_SB(0, 1), b2 + hstep, voffB);
;             PG8_WAIT_V(6); PG8_BAR; PG8_MMA(1, 1, At, B1); PG8_BAR;
;             PG8_LDB(B0, 1, 0); PG8_SCHED; PG8_LDA(At, 1, 0); PG8_STAGE(PG8_SA(0, 1), a2 + hstep, voffA);
;             PG8_WAIT_L(8); PG8_BAR; PG8_WAIT_L(0); PG8_MMA(0, 0, At, B0); PG8_BAR; PG8_SCHED;
;             PG8_LDB(B1, 1, 1); PG8_STAGE(PG8_SB(1, 0), b3, voffB);
;             PG8_BAR; PG8_WAIT_L(0); PG8_MMA(0, 1, At, B1); PG8_BAR;
	s_add_u32 s72, s24, 0x40000
	s_addc_u32 s73, s25, 0
	s_add_i32 s67, s35, s12
	v_lshl_add_u64 v[140:141], s[72:73], 0, v[132:133]
	s_mov_b32 m0, s67
	s_nop 0
	global_load_lds_dwordx4 v[140:141], off
	v_lshl_add_u64 v[140:141], s[72:73], 0, v[130:131]
	s_add_i32 m0, s67, 0x2000
	s_nop 0
	global_load_lds_dwordx4 v[140:141], off
	s_waitcnt vmcnt(6)
	s_barrier
	s_setprio 1
	v_mfma_f32_16x16x32_bf16 v[54:57], v[202:205], v[168:171], v[54:57]
	v_mfma_f32_16x16x32_bf16 v[46:49], v[210:213], v[168:171], v[46:49]
	v_mfma_f32_16x16x32_bf16 v[38:41], v[202:205], v[176:179], v[38:41]
	v_mfma_f32_16x16x32_bf16 v[30:33], v[210:213], v[176:179], v[30:33]
	v_mfma_f32_16x16x32_bf16 v[22:25], v[202:205], v[184:187], v[22:25]
	v_mfma_f32_16x16x32_bf16 v[14:17], v[210:213], v[184:187], v[14:17]
	v_mfma_f32_16x16x32_bf16 v[6:9], v[202:205], v[192:195], v[6:9]
	v_mfma_f32_16x16x32_bf16 v[2:5], v[210:213], v[192:195], v[2:5]
	v_mfma_f32_16x16x32_bf16 v[54:57], v[206:209], v[172:175], v[54:57]
	v_mfma_f32_16x16x32_bf16 v[46:49], v[214:217], v[172:175], v[46:49]
	v_mfma_f32_16x16x32_bf16 v[38:41], v[206:209], v[180:183], v[38:41]
	v_mfma_f32_16x16x32_bf16 v[30:33], v[214:217], v[180:183], v[30:33]
	v_mfma_f32_16x16x32_bf16 v[22:25], v[206:209], v[188:191], v[22:25]
	v_mfma_f32_16x16x32_bf16 v[14:17], v[214:217], v[188:191], v[14:17]
	v_mfma_f32_16x16x32_bf16 v[6:9], v[206:209], v[198:201], v[6:9]
	v_mfma_f32_16x16x32_bf16 v[2:5], v[214:217], v[198:201], v[2:5]
	s_setprio 0
	s_add_i32 s67, 0, 0x18000
	v_add_u32_e32 v134, s67, v145
	s_barrier
	ds_read_b128 v[140:143], v134
	ds_read_b128 v[154:157], v134 offset:1024
	ds_read_b128 v[158:161], v134 offset:2048
	ds_read_b128 v[164:167], v134 offset:3072
	s_add_u32 s26, s26, 0x40000
	s_addc_u32 s27, s27, 0
	s_mov_b32 m0, s29
	v_lshl_add_u64 v[202:203], s[26:27], 0, v[132:133]
	ds_read_b128 v[168:171], v148 offset:32768
	ds_read_b128 v[172:175], v148 offset:33792
	ds_read_b128 v[176:179], v148 offset:34816
	ds_read_b128 v[180:183], v148 offset:35840
	ds_read_b128 v[184:187], v148 offset:36864
	ds_read_b128 v[188:191], v148 offset:37888
	ds_read_b128 v[192:195], v148 offset:38912
	ds_read_b128 v[198:201], v148 offset:39936
	global_load_lds_dwordx4 v[202:203], off
	v_lshl_add_u64 v[202:203], s[26:27], 0, v[130:131]
	s_mov_b32 m0, s30
	s_nop 0
	global_load_lds_dwordx4 v[202:203], off
	s_waitcnt lgkmcnt(8)
	s_barrier
	s_waitcnt lgkmcnt(0)
	s_setprio 1
	s_waitcnt lgkmcnt(0)
	v_mfma_f32_16x16x32_bf16 v[126:129], v[140:143], v[168:171], v[126:129]
	v_mfma_f32_16x16x32_bf16 v[122:125], v[158:161], v[168:171], v[122:125]
	v_mfma_f32_16x16x32_bf16 v[114:117], v[140:143], v[176:179], v[114:117]
	v_mfma_f32_16x16x32_bf16 v[106:109], v[158:161], v[176:179], v[106:109]
	v_mfma_f32_16x16x32_bf16 v[98:101], v[140:143], v[184:187], v[98:101]
	v_mfma_f32_16x16x32_bf16 v[90:93], v[158:161], v[184:187], v[90:93]
	v_mfma_f32_16x16x32_bf16 v[82:85], v[140:143], v[192:195], v[82:85]
	v_mfma_f32_16x16x32_bf16 v[74:77], v[158:161], v[192:195], v[74:77]
	v_mfma_f32_16x16x32_bf16 v[126:129], v[154:157], v[172:175], v[126:129]
	v_mfma_f32_16x16x32_bf16 v[122:125], v[164:167], v[172:175], v[122:125]
	v_mfma_f32_16x16x32_bf16 v[114:117], v[154:157], v[180:183], v[114:117]
	v_mfma_f32_16x16x32_bf16 v[106:109], v[164:167], v[180:183], v[106:109]
	v_mfma_f32_16x16x32_bf16 v[98:101], v[154:157], v[188:191], v[98:101]
	v_mfma_f32_16x16x32_bf16 v[90:93], v[164:167], v[188:191], v[90:93]
	v_mfma_f32_16x16x32_bf16 v[82:85], v[154:157], v[198:201], v[82:85]
	v_mfma_f32_16x16x32_bf16 v[74:77], v[164:167], v[198:201], v[74:77]
	s_setprio 0
	s_barrier
	s_add_i32 s26, 0, 0x1c000
	s_add_i32 s27, s67, s12
	v_add_u32_e32 v134, s26, v145
	v_lshl_add_u64 v[150:151], v[150:151], 0, s[10:11]
	s_mov_b32 m0, s27
	ds_read_b128 v[202:205], v134
	ds_read_b128 v[206:209], v134 offset:1024
	ds_read_b128 v[210:213], v134 offset:2048
	ds_read_b128 v[214:217], v134 offset:3072
	global_load_lds_dwordx4 v[150:151], off
	v_lshl_add_u64 v[150:151], v[218:219], 0, s[10:11]
	s_add_i32 m0, s27, 0x2000
	s_nop 0
	global_load_lds_dwordx4 v[150:151], off
	s_barrier
	s_waitcnt lgkmcnt(0)
	s_setprio 1
	s_waitcnt lgkmcnt(0)
	v_mfma_f32_16x16x32_bf16 v[118:121], v[202:205], v[168:171], v[118:121]
	v_mfma_f32_16x16x32_bf16 v[110:113], v[210:213], v[168:171], v[110:113]
	v_mfma_f32_16x16x32_bf16 v[102:105], v[202:205], v[176:179], v[102:105]
	v_mfma_f32_16x16x32_bf16 v[94:97], v[210:213], v[176:179], v[94:97]
	v_mfma_f32_16x16x32_bf16 v[86:89], v[202:205], v[184:187], v[86:89]
	v_mfma_f32_16x16x32_bf16 v[78:81], v[210:213], v[184:187], v[78:81]
	v_mfma_f32_16x16x32_bf16 v[70:73], v[202:205], v[192:195], v[70:73]
	v_mfma_f32_16x16x32_bf16 v[66:69], v[210:213], v[192:195], v[66:69]
	v_mfma_f32_16x16x32_bf16 v[118:121], v[206:209], v[172:175], v[118:121]
	v_mfma_f32_16x16x32_bf16 v[110:113], v[214:217], v[172:175], v[110:113]
	v_mfma_f32_16x16x32_bf16 v[102:105], v[206:209], v[180:183], v[102:105]
	v_mfma_f32_16x16x32_bf16 v[94:97], v[214:217], v[180:183], v[94:97]
	v_mfma_f32_16x16x32_bf16 v[86:89], v[206:209], v[188:191], v[86:89]
	v_mfma_f32_16x16x32_bf16 v[78:81], v[214:217], v[188:191], v[78:81]
	v_mfma_f32_16x16x32_bf16 v[70:73], v[206:209], v[198:201], v[70:73]
	v_mfma_f32_16x16x32_bf16 v[66:69], v[214:217], v[198:201], v[66:69]
	s_setprio 0
	s_mov_b32 m0, s33
	v_lshl_add_u64 v[150:151], v[220:221], 0, s[10:11]
	s_barrier
	ds_read_b128 v[168:171], v148 offset:49152
	ds_read_b128 v[172:175], v148 offset:50176
	ds_read_b128 v[176:179], v148 offset:51200
	ds_read_b128 v[180:183], v148 offset:52224
	ds_read_b128 v[184:187], v148 offset:53248
	ds_read_b128 v[188:191], v148 offset:54272
	ds_read_b128 v[192:195], v148 offset:55296
	ds_read_b128 v[198:201], v148 offset:56320
	global_load_lds_dwordx4 v[150:151], off
	v_lshl_add_u64 v[150:151], v[222:223], 0, s[10:11]
	s_mov_b32 m0, s34
	s_nop 0
	global_load_lds_dwordx4 v[150:151], off
	s_barrier
; DI unsigned pk_bf16(float a, float b) { f32x2 v = {a, b}; bf2_t r = __builtin_convertvector(v, bf2_t); return __builtin_bit_cast(unsigned, r); }
; DI float bflo(unsigned u) { return __uint_as_float(u << 16); }
; DI float bfhi(unsigned u) { return __uint_as_float(u & 0xffff0000u); }
; #define PG8_STAGE(bufoff, gbase, voff) do { _Pragma("unroll") for (int _i = 0; _i < 2; ++_i) \
;         __builtin_amdgcn_global_load_lds((const unsigned*)((const char*)(gbase) + (voff)[_i]), (LAS unsigned*)(lds + (bufoff) + ldsw + _i * 8192), 16, 0, 0); } while (0)
; #define PG8_LDA(dst, b, h) do { _Pragma("unroll") for (int m = 0; m < 4; ++m) _Pragma("unroll") for (int k = 0; k < 2; ++k) dst[m][k] = *(const LAS bf16x8*)(lds + PG8_SA(b, h) + aoff + m * 2048 + k * 1024); } while (0)
; #define PG8_WAIT_V(n) asm volatile("s_waitcnt vmcnt(" #n ")" ::: "memory")
;     DI void operator()(const f32x4 (&acc)[2][2][4][2], const Unit& u, int wr, int wc, int fr, int fq) const {
;         const int row0 = u.pm * BM + wr * 64 + fr, col0 = u.pn * BM + wc * 32 + 4 * fq;
; #pragma unroll
;         for (int ai = 0; ai < 2; ++ai)
; #pragma unroll
;             for (int m = 0; m < 4; ++m) { const size_t o = (size_t)(row0 + ai * HALF + m * 16) * 1024 + col0;
; #pragma unroll
;                 for (int bj = 0; bj < 2; ++bj)
; #pragma unroll
;                     for (int n = 0; n < 2; ++n) { const size_t oo = o + bj * HALF + n * 16; f32x4 rv;
;                         if (RES_BF16) { const u32x2 t = *(const u32x2*)((const bf16_t*)res + oo); rv = (f32x4){bflo(t.x), bfhi(t.x), bflo(t.y), bfhi(t.y)}; }
;                         else rv = *(const f32x4*)((const float*)res + oo);
;                         const f32x4 v = acc[ai][bj][m][n] + rv; u32x2 w; w.x = pk_bf16(v.x, v.y); w.y = pk_bf16(v.z, v.w);
;                         *(u32x2*)(O + oo) = w; } }
; template <class Epi, class Sched>
; DI void gemm_phase(LAS unsigned char* lds, const Gemm g, const Sched& S, const Epi& E) {
;     ...
;             PG8_BAR; PG8_WAIT_L(0); PG8_MMA(0, 1, At, B1); PG8_BAR;
;             PG8_LDA(At, 1, 1); PG8_STAGE(PG8_SA(1, 0), a3, voffA);
;             PG8_BAR; PG8_WAIT_L(0); PG8_MMA(1, 0, At, B0); PG8_BAR; PG8_SCHED;
;             PG8_STAGE(PG8_SB(1, 1), b3 + hstep, voffB);
;             PG8_WAIT_V(6); PG8_BAR; PG8_MMA(1, 1, At, B1); PG8_BAR;
;         }
;         E(acc, cur, wr, wc, fr, fq);
	s_waitcnt lgkmcnt(0)
	s_setprio 1
	s_waitcnt lgkmcnt(0)
	v_mfma_f32_16x16x32_bf16 v[62:65], v[140:143], v[168:171], v[62:65]
	v_mfma_f32_16x16x32_bf16 v[58:61], v[158:161], v[168:171], v[58:61]
	v_mfma_f32_16x16x32_bf16 v[50:53], v[140:143], v[176:179], v[50:53]
	v_mfma_f32_16x16x32_bf16 v[42:45], v[158:161], v[176:179], v[42:45]
	v_mfma_f32_16x16x32_bf16 v[34:37], v[140:143], v[184:187], v[34:37]
	v_mfma_f32_16x16x32_bf16 v[26:29], v[158:161], v[184:187], v[26:29]
	v_mfma_f32_16x16x32_bf16 v[18:21], v[140:143], v[192:195], v[18:21]
	v_mfma_f32_16x16x32_bf16 v[10:13], v[158:161], v[192:195], v[10:13]
	v_mfma_f32_16x16x32_bf16 v[62:65], v[154:157], v[172:175], v[62:65]
	v_mfma_f32_16x16x32_bf16 v[58:61], v[164:167], v[172:175], v[58:61]
	v_mfma_f32_16x16x32_bf16 v[50:53], v[154:157], v[180:183], v[50:53]
	v_mfma_f32_16x16x32_bf16 v[42:45], v[164:167], v[180:183], v[42:45]
	v_mfma_f32_16x16x32_bf16 v[34:37], v[154:157], v[188:191], v[34:37]
	v_mfma_f32_16x16x32_bf16 v[26:29], v[164:167], v[188:191], v[26:29]
	v_mfma_f32_16x16x32_bf16 v[18:21], v[154:157], v[198:201], v[18:21]
	v_mfma_f32_16x16x32_bf16 v[10:13], v[164:167], v[198:201], v[10:13]
	s_setprio 0
	s_barrier
	s_add_u32 s24, s24, 0x40080
	s_addc_u32 s25, s25, 0
	s_add_i32 s26, s26, s12
	v_lshl_add_u64 v[140:141], s[24:25], 0, v[132:133]
	s_mov_b32 m0, s26
	s_nop 0
	global_load_lds_dwordx4 v[140:141], off
	v_lshl_add_u64 v[140:141], s[24:25], 0, v[130:131]
	s_add_i32 m0, s26, 0x2000
	s_nop 0
	global_load_lds_dwordx4 v[140:141], off
	s_waitcnt vmcnt(6)
	s_barrier
	s_setprio 1
	v_mfma_f32_16x16x32_bf16 v[54:57], v[202:205], v[168:171], v[54:57]
	v_mfma_f32_16x16x32_bf16 v[46:49], v[210:213], v[168:171], v[46:49]
	v_mfma_f32_16x16x32_bf16 v[38:41], v[202:205], v[176:179], v[38:41]
	v_mfma_f32_16x16x32_bf16 v[30:33], v[210:213], v[176:179], v[30:33]
	v_mfma_f32_16x16x32_bf16 v[22:25], v[202:205], v[184:187], v[22:25]
	v_mfma_f32_16x16x32_bf16 v[14:17], v[210:213], v[184:187], v[14:17]
	v_mfma_f32_16x16x32_bf16 v[6:9], v[202:205], v[192:195], v[6:9]
	v_mfma_f32_16x16x32_bf16 v[2:5], v[210:213], v[192:195], v[2:5]
	v_mfma_f32_16x16x32_bf16 v[54:57], v[206:209], v[172:175], v[54:57]
	v_mfma_f32_16x16x32_bf16 v[46:49], v[214:217], v[172:175], v[46:49]
	v_mfma_f32_16x16x32_bf16 v[38:41], v[206:209], v[180:183], v[38:41]
	v_mfma_f32_16x16x32_bf16 v[30:33], v[214:217], v[180:183], v[30:33]
	v_mfma_f32_16x16x32_bf16 v[22:25], v[206:209], v[188:191], v[22:25]
	v_mfma_f32_16x16x32_bf16 v[14:17], v[214:217], v[188:191], v[14:17]
	v_mfma_f32_16x16x32_bf16 v[6:9], v[206:209], v[198:201], v[6:9]
	v_mfma_f32_16x16x32_bf16 v[2:5], v[214:217], v[198:201], v[2:5]
	s_setprio 0
	s_add_i32 s66, s66, 2
	s_add_u32 s22, s22, 0x100
	s_addc_u32 s23, s23, 0
	s_add_u32 s58, s58, 0x100
	s_addc_u32 s59, s59, 0
	s_cmp_gt_u32 s66, 13
	s_barrier
	s_cbranch_scc0 .LBB0_1007
	v_lshl_add_u32 v224, s43, 8, v144
	v_lshl_or_b32 v243, s42, 8, v146
	v_lshl_or_b32 v224, v224, 10, v243
	s_and_b64 vcc, exec, s[20:21]
	s_mov_b32 s42, s40
	s_mov_b32 s43, s41
	s_mov_b64 s[22:23], 0x2c000
	v_lshlrev_b32_e32 v225, 2, v224
	v_lshlrev_b32_e32 v233, 1, v224
	v_add_u32_e32 v234, 0x4000, v224
	v_lshlrev_b32_e32 v226, 2, v234
	v_lshlrev_b32_e32 v234, 1, v234
	v_add_u32_e32 v235, 0x8000, v224
	v_lshlrev_b32_e32 v227, 2, v235
	v_lshlrev_b32_e32 v235, 1, v235
	v_add_u32_e32 v236, 0xc000, v224
	v_lshlrev_b32_e32 v228, 2, v236
	v_lshlrev_b32_e32 v236, 1, v236
	v_add_u32_e32 v237, 0x20000, v224
	v_lshlrev_b32_e32 v229, 2, v237
	v_lshlrev_b32_e32 v237, 1, v237
	v_add_u32_e32 v240, 0x24000, v224
	v_lshlrev_b32_e32 v230, 2, v240
	v_lshlrev_b32_e32 v240, 1, v240
	v_add_u32_e32 v241, 0x28000, v224
	v_lshlrev_b32_e32 v231, 2, v241
	v_lshlrev_b32_e32 v241, 1, v241
	v_add_u32_e32 v242, 0x2c000, v224
	v_lshlrev_b32_e32 v232, 2, v242
	v_lshlrev_b32_e32 v242, 1, v242
	global_load_dwordx4 v[140:143], v225, s[60:61]
	global_load_dwordx4 v[154:157], v225, s[60:61] offset:64
	global_load_dwordx4 v[158:161], v225, s[60:61] offset:512
	global_load_dwordx4 v[164:167], v225, s[60:61] offset:576
	global_load_dwordx4 v[168:171], v226, s[60:61]
	global_load_dwordx4 v[172:175], v226, s[60:61] offset:64
	global_load_dwordx4 v[176:179], v226, s[60:61] offset:512
	global_load_dwordx4 v[180:183], v226, s[60:61] offset:576
	global_load_dwordx4 v[184:187], v227, s[60:61]
	global_load_dwordx4 v[188:191], v227, s[60:61] offset:64
	global_load_dwordx4 v[192:195], v227, s[60:61] offset:512
	global_load_dwordx4 v[198:201], v227, s[60:61] offset:576
	global_load_dwordx4 v[202:205], v228, s[60:61]
	global_load_dwordx4 v[206:209], v228, s[60:61] offset:64
	global_load_dwordx4 v[210:213], v228, s[60:61] offset:512
	global_load_dwordx4 v[214:217], v228, s[60:61] offset:576
	s_waitcnt vmcnt(12)
	v_pk_add_f32 v[128:129], v[128:129], v[142:143]
	v_pk_add_f32 v[126:127], v[126:127], v[140:141]
	v_pk_add_f32 v[124:125], v[124:125], v[156:157]
	v_pk_add_f32 v[122:123], v[122:123], v[154:155]
	v_pk_add_f32 v[120:121], v[120:121], v[160:161]
	v_pk_add_f32 v[118:119], v[118:119], v[158:159]
	v_pk_add_f32 v[112:113], v[112:113], v[166:167]
	v_pk_add_f32 v[110:111], v[110:111], v[164:165]
	v_cvt_pk_bf16_f32 v126, v126, v127
	v_cvt_pk_bf16_f32 v127, v128, v129
	v_cvt_pk_bf16_f32 v122, v122, v123
	v_cvt_pk_bf16_f32 v123, v124, v125
	v_cvt_pk_bf16_f32 v118, v118, v119
	v_cvt_pk_bf16_f32 v119, v120, v121
	v_cvt_pk_bf16_f32 v110, v110, v111
	v_cvt_pk_bf16_f32 v111, v112, v113
	global_store_dwordx2 v233, v[126:127], s[48:49] nt
	global_store_dwordx2 v233, v[122:123], s[48:49] offset:32 nt
	global_store_dwordx2 v233, v[118:119], s[48:49] offset:256 nt
	global_store_dwordx2 v233, v[110:111], s[48:49] offset:288 nt
	global_load_dwordx4 v[140:143], v229, s[60:61]
	global_load_dwordx4 v[154:157], v229, s[60:61] offset:64
	global_load_dwordx4 v[158:161], v229, s[60:61] offset:512
	global_load_dwordx4 v[164:167], v229, s[60:61] offset:576
	s_waitcnt vmcnt(16)
; DI unsigned pk_bf16(float a, float b) { f32x2 v = {a, b}; bf2_t r = __builtin_convertvector(v, bf2_t); return __builtin_bit_cast(unsigned, r); }
; DI float bflo(unsigned u) { return __uint_as_float(u << 16); }
; DI float bfhi(unsigned u) { return __uint_as_float(u & 0xffff0000u); }
; #define PG8_WAIT_V(n) asm volatile("s_waitcnt vmcnt(" #n ")" ::: "memory")
; #define PG8_BAR __builtin_amdgcn_s_barrier()
;     DI void operator()(const f32x4 (&acc)[2][2][4][2], const Unit& u, int wr, int wc, int fr, int fq) const {
;     ...
;             for (int m = 0; m < 4; ++m) { const size_t o = (size_t)(row0 + ai * HALF + m * 16) * 1024 + col0;
; #pragma unroll
;                 for (int bj = 0; bj < 2; ++bj)
; #pragma unroll
;                     for (int n = 0; n < 2; ++n) { const size_t oo = o + bj * HALF + n * 16; f32x4 rv;
;                         if (RES_BF16) { const u32x2 t = *(const u32x2*)((const bf16_t*)res + oo); rv = (f32x4){bflo(t.x), bfhi(t.x), bflo(t.y), bfhi(t.y)}; }
;                         else rv = *(const f32x4*)((const float*)res + oo);
;                         const f32x4 v = acc[ai][bj][m][n] + rv; u32x2 w; w.x = pk_bf16(v.x, v.y); w.y = pk_bf16(v.z, v.w);
;                         *(u32x2*)(O + oo) = w; } }
; template <class Epi, class Sched>
; DI void gemm_phase(LAS unsigned char* lds, const Gemm g, const Sched& S, const Epi& E) {
;     ...
;         if (!has_next) break;
; #pragma unroll
;         for (int a = 0; a < 2; ++a)
; #pragma unroll
;             for (int b = 0; b < 2; ++b)
; #pragma unroll
;                 for (int m = 0; m < 4; ++m)
; #pragma unroll
;                     for (int n = 0; n < 2; ++n) acc[a][b][m][n] = (f32x4){0.f, 0.f, 0.f, 0.f};
;         cur = nxt; cA = nA; cB = nB; ++ui;
;     }
;     PG8_WAIT_V(0);
;     if (wr == 0) PG8_BAR;
;     PG8_BAR;
	v_pk_add_f32 v[116:117], v[116:117], v[170:171]
	v_pk_add_f32 v[114:115], v[114:115], v[168:169]
	v_pk_add_f32 v[108:109], v[108:109], v[174:175]
	v_pk_add_f32 v[106:107], v[106:107], v[172:173]
	v_pk_add_f32 v[104:105], v[104:105], v[178:179]
	v_pk_add_f32 v[102:103], v[102:103], v[176:177]
	v_pk_add_f32 v[96:97], v[96:97], v[182:183]
	v_pk_add_f32 v[94:95], v[94:95], v[180:181]
	v_cvt_pk_bf16_f32 v114, v114, v115
	v_cvt_pk_bf16_f32 v115, v116, v117
	v_cvt_pk_bf16_f32 v106, v106, v107
	v_cvt_pk_bf16_f32 v107, v108, v109
	v_cvt_pk_bf16_f32 v102, v102, v103
	v_cvt_pk_bf16_f32 v103, v104, v105
	v_cvt_pk_bf16_f32 v94, v94, v95
	v_cvt_pk_bf16_f32 v95, v96, v97
	global_store_dwordx2 v234, v[114:115], s[48:49] nt
	global_store_dwordx2 v234, v[106:107], s[48:49] offset:32 nt
	global_store_dwordx2 v234, v[102:103], s[48:49] offset:256 nt
	global_store_dwordx2 v234, v[94:95], s[48:49] offset:288 nt
	global_load_dwordx4 v[168:171], v230, s[60:61]
	global_load_dwordx4 v[172:175], v230, s[60:61] offset:64
	global_load_dwordx4 v[176:179], v230, s[60:61] offset:512
	global_load_dwordx4 v[180:183], v230, s[60:61] offset:576
	s_waitcnt vmcnt(20)
	v_pk_add_f32 v[100:101], v[100:101], v[186:187]
	v_pk_add_f32 v[98:99], v[98:99], v[184:185]
	v_pk_add_f32 v[92:93], v[92:93], v[190:191]
	v_pk_add_f32 v[90:91], v[90:91], v[188:189]
	v_pk_add_f32 v[88:89], v[88:89], v[194:195]
	v_pk_add_f32 v[86:87], v[86:87], v[192:193]
	v_pk_add_f32 v[80:81], v[80:81], v[200:201]
	v_pk_add_f32 v[78:79], v[78:79], v[198:199]
	v_cvt_pk_bf16_f32 v98, v98, v99
	v_cvt_pk_bf16_f32 v99, v100, v101
	v_cvt_pk_bf16_f32 v90, v90, v91
	v_cvt_pk_bf16_f32 v91, v92, v93
	v_cvt_pk_bf16_f32 v86, v86, v87
	v_cvt_pk_bf16_f32 v87, v88, v89
	v_cvt_pk_bf16_f32 v78, v78, v79
	v_cvt_pk_bf16_f32 v79, v80, v81
	global_store_dwordx2 v235, v[98:99], s[48:49] nt
	global_store_dwordx2 v235, v[90:91], s[48:49] offset:32 nt
	global_store_dwordx2 v235, v[86:87], s[48:49] offset:256 nt
	global_store_dwordx2 v235, v[78:79], s[48:49] offset:288 nt
	global_load_dwordx4 v[184:187], v231, s[60:61]
	global_load_dwordx4 v[188:191], v231, s[60:61] offset:64
	global_load_dwordx4 v[192:195], v231, s[60:61] offset:512
	global_load_dwordx4 v[198:201], v231, s[60:61] offset:576
	s_waitcnt vmcnt(24)
	v_pk_add_f32 v[84:85], v[84:85], v[204:205]
	v_pk_add_f32 v[82:83], v[82:83], v[202:203]
	v_pk_add_f32 v[76:77], v[76:77], v[208:209]
	v_pk_add_f32 v[74:75], v[74:75], v[206:207]
	v_pk_add_f32 v[72:73], v[72:73], v[212:213]
	v_pk_add_f32 v[70:71], v[70:71], v[210:211]
	v_pk_add_f32 v[68:69], v[68:69], v[216:217]
	v_pk_add_f32 v[66:67], v[66:67], v[214:215]
	v_cvt_pk_bf16_f32 v82, v82, v83
	v_cvt_pk_bf16_f32 v83, v84, v85
	v_cvt_pk_bf16_f32 v74, v74, v75
	v_cvt_pk_bf16_f32 v75, v76, v77
	v_cvt_pk_bf16_f32 v70, v70, v71
	v_cvt_pk_bf16_f32 v71, v72, v73
	v_cvt_pk_bf16_f32 v66, v66, v67
	v_cvt_pk_bf16_f32 v67, v68, v69
	global_store_dwordx2 v236, v[82:83], s[48:49] nt
	global_store_dwordx2 v236, v[74:75], s[48:49] offset:32 nt
	global_store_dwordx2 v236, v[70:71], s[48:49] offset:256 nt
	global_store_dwordx2 v236, v[66:67], s[48:49] offset:288 nt
	global_load_dwordx4 v[202:205], v232, s[60:61]
	global_load_dwordx4 v[206:209], v232, s[60:61] offset:64
	global_load_dwordx4 v[210:213], v232, s[60:61] offset:512
	global_load_dwordx4 v[214:217], v232, s[60:61] offset:576
	s_waitcnt vmcnt(24)
	v_pk_add_f32 v[64:65], v[64:65], v[142:143]
	v_pk_add_f32 v[62:63], v[62:63], v[140:141]
	v_pk_add_f32 v[60:61], v[60:61], v[156:157]
	v_pk_add_f32 v[58:59], v[58:59], v[154:155]
	v_pk_add_f32 v[56:57], v[56:57], v[160:161]
	v_pk_add_f32 v[54:55], v[54:55], v[158:159]
	v_pk_add_f32 v[48:49], v[48:49], v[166:167]
	v_pk_add_f32 v[46:47], v[46:47], v[164:165]
	v_cvt_pk_bf16_f32 v62, v62, v63
	v_cvt_pk_bf16_f32 v63, v64, v65
	v_cvt_pk_bf16_f32 v58, v58, v59
	v_cvt_pk_bf16_f32 v59, v60, v61
	v_cvt_pk_bf16_f32 v54, v54, v55
	v_cvt_pk_bf16_f32 v55, v56, v57
	v_cvt_pk_bf16_f32 v46, v46, v47
	v_cvt_pk_bf16_f32 v47, v48, v49
	global_store_dwordx2 v237, v[62:63], s[48:49] nt
	global_store_dwordx2 v237, v[58:59], s[48:49] offset:32 nt
	global_store_dwordx2 v237, v[54:55], s[48:49] offset:256 nt
	global_store_dwordx2 v237, v[46:47], s[48:49] offset:288 nt
	s_waitcnt vmcnt(20)
	v_pk_add_f32 v[52:53], v[52:53], v[170:171]
	v_pk_add_f32 v[50:51], v[50:51], v[168:169]
	v_pk_add_f32 v[44:45], v[44:45], v[174:175]
	v_pk_add_f32 v[42:43], v[42:43], v[172:173]
	v_pk_add_f32 v[40:41], v[40:41], v[178:179]
	v_pk_add_f32 v[38:39], v[38:39], v[176:177]
	v_pk_add_f32 v[32:33], v[32:33], v[182:183]
	v_pk_add_f32 v[30:31], v[30:31], v[180:181]
	v_cvt_pk_bf16_f32 v50, v50, v51
	v_cvt_pk_bf16_f32 v51, v52, v53
	v_cvt_pk_bf16_f32 v42, v42, v43
	v_cvt_pk_bf16_f32 v43, v44, v45
	v_cvt_pk_bf16_f32 v38, v38, v39
	v_cvt_pk_bf16_f32 v39, v40, v41
	v_cvt_pk_bf16_f32 v30, v30, v31
	v_cvt_pk_bf16_f32 v31, v32, v33
	global_store_dwordx2 v240, v[50:51], s[48:49] nt
	global_store_dwordx2 v240, v[42:43], s[48:49] offset:32 nt
	global_store_dwordx2 v240, v[38:39], s[48:49] offset:256 nt
	global_store_dwordx2 v240, v[30:31], s[48:49] offset:288 nt
	s_waitcnt vmcnt(16)
	v_pk_add_f32 v[36:37], v[36:37], v[186:187]
	v_pk_add_f32 v[34:35], v[34:35], v[184:185]
	v_pk_add_f32 v[28:29], v[28:29], v[190:191]
	v_pk_add_f32 v[26:27], v[26:27], v[188:189]
	v_pk_add_f32 v[24:25], v[24:25], v[194:195]
	v_pk_add_f32 v[22:23], v[22:23], v[192:193]
	v_pk_add_f32 v[16:17], v[16:17], v[200:201]
	v_pk_add_f32 v[14:15], v[14:15], v[198:199]
	v_cvt_pk_bf16_f32 v34, v34, v35
	v_cvt_pk_bf16_f32 v35, v36, v37
	v_cvt_pk_bf16_f32 v26, v26, v27
	v_cvt_pk_bf16_f32 v27, v28, v29
	v_cvt_pk_bf16_f32 v22, v22, v23
	v_cvt_pk_bf16_f32 v23, v24, v25
	v_cvt_pk_bf16_f32 v14, v14, v15
	v_cvt_pk_bf16_f32 v15, v16, v17
	global_store_dwordx2 v241, v[34:35], s[48:49] nt
	global_store_dwordx2 v241, v[26:27], s[48:49] offset:32 nt
	global_store_dwordx2 v241, v[22:23], s[48:49] offset:256 nt
	global_store_dwordx2 v241, v[14:15], s[48:49] offset:288 nt
	s_waitcnt vmcnt(12)
	v_pk_add_f32 v[20:21], v[20:21], v[204:205]
	v_pk_add_f32 v[18:19], v[18:19], v[202:203]
	v_pk_add_f32 v[12:13], v[12:13], v[208:209]
	v_pk_add_f32 v[10:11], v[10:11], v[206:207]
	v_pk_add_f32 v[8:9], v[8:9], v[212:213]
	v_pk_add_f32 v[6:7], v[6:7], v[210:211]
	v_pk_add_f32 v[4:5], v[4:5], v[216:217]
	v_pk_add_f32 v[2:3], v[2:3], v[214:215]
	v_cvt_pk_bf16_f32 v18, v18, v19
	v_cvt_pk_bf16_f32 v19, v20, v21
	v_cvt_pk_bf16_f32 v10, v10, v11
	v_cvt_pk_bf16_f32 v11, v12, v13
	v_cvt_pk_bf16_f32 v6, v6, v7
	v_cvt_pk_bf16_f32 v7, v8, v9
	v_cvt_pk_bf16_f32 v2, v2, v3
	v_cvt_pk_bf16_f32 v3, v4, v5
	global_store_dwordx2 v242, v[18:19], s[48:49] nt
	global_store_dwordx2 v242, v[10:11], s[48:49] offset:32 nt
	global_store_dwordx2 v242, v[6:7], s[48:49] offset:256 nt
	global_store_dwordx2 v242, v[2:3], s[48:49] offset:288 nt
	s_cbranch_vccz .LBB0_1006
	s_waitcnt vmcnt(0)
	s_cmpk_gt_u32 s3, 0xff
	s_cbranch_scc1 .LBB0_1011
	s_barrier

; #define PG8_STAGE(bufoff, gbase, voff) do { _Pragma("unroll") for (int _i = 0; _i < 2; ++_i) \
;         __builtin_amdgcn_global_load_lds((const unsigned*)((const char*)(gbase) + (voff)[_i]), (LAS unsigned*)(lds + (bufoff) + ldsw + _i * 8192), 16, 0, 0); } while (0)
; #define PG8_LDA(dst, b, h) do { _Pragma("unroll") for (int m = 0; m < 4; ++m) _Pragma("unroll") for (int k = 0; k < 2; ++k) dst[m][k] = *(const LAS bf16x8*)(lds + PG8_SA(b, h) + aoff + m * 2048 + k * 1024); } while (0)
; #define PG8_LDB(dst, b, h) do { _Pragma("unroll") for (int n = 0; n < 2; ++n) _Pragma("unroll") for (int k = 0; k < 2; ++k) dst[n][k] = *(const LAS bf16x8*)(lds + PG8_SB(b, h) + boff + n * 2048 + k * 1024); } while (0)
; #define PG8_MMA(ai, bj, At, Bt) do { __builtin_amdgcn_s_setprio(1); _Pragma("unroll") for (int m = 0; m < 4; ++m) _Pragma("unroll") for (int n = 0; n < 2; ++n) _Pragma("unroll") for (int k = 0; k < 2; ++k) \
;         acc[ai][bj][m][n] = __builtin_amdgcn_mfma_f32_16x16x32_bf16(Bt[n][k], At[m][k], acc[ai][bj][m][n], 0, 0, 0); __builtin_amdgcn_s_setprio(0); } while (0)
; #define PG8_WAIT_L(n) asm volatile("s_waitcnt lgkmcnt(" #n ")" ::: "memory")
; #define PG8_BAR __builtin_amdgcn_s_barrier()
; #define PG8_SCHED __builtin_amdgcn_sched_barrier(0)
; template <class Epi, class Sched>
; DI void gemm_phase(LAS unsigned char* lds, const Gemm g, const Sched& S, const Epi& E) {
;     ...
;             PG8_LDB(B0, 0, 0); PG8_SCHED; PG8_LDA(At, 0, 0); PG8_STAGE(PG8_SA(1, 1), a1 + hstep, voffA);
;             PG8_WAIT_L(8); PG8_BAR; PG8_WAIT_L(0); PG8_MMA(0, 0, At, B0); PG8_BAR; PG8_SCHED;
;             PG8_LDB(B1, 0, 1); PG8_STAGE(PG8_SB(0, 0), b2, voffB);
;             PG8_BAR; PG8_WAIT_L(0); PG8_MMA(0, 1, At, B1); PG8_BAR;
;             PG8_LDA(At, 0, 1); PG8_STAGE(PG8_SA(0, 0), a2, voffA);
;             PG8_BAR; PG8_WAIT_L(0); PG8_MMA(1, 0, At, B0); PG8_BAR; PG8_SCHED;
.LBB0_1523:
	ds_read_b128 v[140:143], v146
	ds_read_b128 v[150:153], v146 offset:1024
	ds_read_b128 v[154:157], v146 offset:2048
	ds_read_b128 v[158:161], v146 offset:3072
	s_add_u32 s50, s42, 0xfff80080
	s_addc_u32 s51, s43, -1
	s_cmp_eq_u32 s73, 28
	s_cselect_b32 s53, s67, s51
	s_cselect_b32 s52, s68, s50
	s_cselect_b32 s51, s69, s72
	s_cselect_b32 s50, s70, s71
	v_lshl_add_u64 v[202:203], s[42:43], 0, v[136:137]
	s_add_i32 m0, s47, 0xc000
	ds_read_b128 v[168:171], v147
	ds_read_b128 v[172:175], v147 offset:1024
	ds_read_b128 v[176:179], v147 offset:2048
	ds_read_b128 v[180:183], v147 offset:3072
	ds_read_b128 v[184:187], v147 offset:4096
	ds_read_b128 v[188:191], v147 offset:5120
	ds_read_b128 v[192:195], v147 offset:6144
	ds_read_b128 v[198:201], v147 offset:7168
	global_load_lds_dwordx4 v[202:203], off
	v_lshl_add_u64 v[202:203], s[42:43], 0, v[138:139]
	s_add_i32 m0, s47, 0xe000
	s_nop 0
	global_load_lds_dwordx4 v[202:203], off
	s_waitcnt lgkmcnt(8)
	s_barrier
	s_waitcnt lgkmcnt(0)
	s_setprio 1
	s_waitcnt lgkmcnt(0)
	v_mfma_f32_16x16x32_bf16 v[126:129], v[140:143], v[168:171], v[126:129]
	v_mfma_f32_16x16x32_bf16 v[122:125], v[154:157], v[168:171], v[122:125]
	v_mfma_f32_16x16x32_bf16 v[110:113], v[140:143], v[176:179], v[110:113]
	v_mfma_f32_16x16x32_bf16 v[106:109], v[154:157], v[176:179], v[106:109]
	v_mfma_f32_16x16x32_bf16 v[94:97], v[140:143], v[184:187], v[94:97]
	v_mfma_f32_16x16x32_bf16 v[90:93], v[154:157], v[184:187], v[90:93]
	v_mfma_f32_16x16x32_bf16 v[78:81], v[140:143], v[192:195], v[78:81]
	v_mfma_f32_16x16x32_bf16 v[74:77], v[154:157], v[192:195], v[74:77]
	v_mfma_f32_16x16x32_bf16 v[126:129], v[150:153], v[172:175], v[126:129]
	v_mfma_f32_16x16x32_bf16 v[122:125], v[158:161], v[172:175], v[122:125]
	v_mfma_f32_16x16x32_bf16 v[110:113], v[150:153], v[180:183], v[110:113]
	v_mfma_f32_16x16x32_bf16 v[106:109], v[158:161], v[180:183], v[106:109]
	v_mfma_f32_16x16x32_bf16 v[94:97], v[150:153], v[188:191], v[94:97]
	v_mfma_f32_16x16x32_bf16 v[90:93], v[158:161], v[188:191], v[90:93]
	v_mfma_f32_16x16x32_bf16 v[78:81], v[150:153], v[198:201], v[78:81]
	v_mfma_f32_16x16x32_bf16 v[74:77], v[158:161], v[198:201], v[74:77]
	s_setprio 0
	s_barrier
	s_add_i32 s83, s63, s33
	v_lshl_add_u64 v[218:219], s[50:51], 0, v[132:133]
	s_mov_b32 m0, s83
	ds_read_b128 v[202:205], v148
	ds_read_b128 v[206:209], v148 offset:1024
	ds_read_b128 v[210:213], v148 offset:2048
	ds_read_b128 v[214:217], v148 offset:3072
	global_load_lds_dwordx4 v[218:219], off
	v_lshl_add_u64 v[220:221], s[50:51], 0, v[130:131]
	s_add_i32 m0, s83, 0x2000
	s_nop 0
	global_load_lds_dwordx4 v[220:221], off
	s_barrier
	s_waitcnt lgkmcnt(0)
	s_setprio 1
	s_waitcnt lgkmcnt(0)
	v_mfma_f32_16x16x32_bf16 v[118:121], v[202:205], v[168:171], v[118:121]
	v_mfma_f32_16x16x32_bf16 v[114:117], v[210:213], v[168:171], v[114:117]
	v_mfma_f32_16x16x32_bf16 v[102:105], v[202:205], v[176:179], v[102:105]
	v_mfma_f32_16x16x32_bf16 v[98:101], v[210:213], v[176:179], v[98:101]
	v_mfma_f32_16x16x32_bf16 v[86:89], v[202:205], v[184:187], v[86:89]
	v_mfma_f32_16x16x32_bf16 v[82:85], v[210:213], v[184:187], v[82:85]
	v_mfma_f32_16x16x32_bf16 v[70:73], v[202:205], v[192:195], v[70:73]
	v_mfma_f32_16x16x32_bf16 v[66:69], v[210:213], v[192:195], v[66:69]
	v_mfma_f32_16x16x32_bf16 v[118:121], v[206:209], v[172:175], v[118:121]
	v_mfma_f32_16x16x32_bf16 v[114:117], v[214:217], v[172:175], v[114:117]
	v_mfma_f32_16x16x32_bf16 v[102:105], v[206:209], v[180:183], v[102:105]
	v_mfma_f32_16x16x32_bf16 v[98:101], v[214:217], v[180:183], v[98:101]
	v_mfma_f32_16x16x32_bf16 v[86:89], v[206:209], v[188:191], v[86:89]
	v_mfma_f32_16x16x32_bf16 v[82:85], v[214:217], v[188:191], v[82:85]
	v_mfma_f32_16x16x32_bf16 v[70:73], v[206:209], v[198:201], v[70:73]
	v_mfma_f32_16x16x32_bf16 v[66:69], v[214:217], v[198:201], v[66:69]
	s_setprio 0
	s_mov_b32 m0, s47
	v_lshl_add_u64 v[222:223], s[52:53], 0, v[132:133]
	s_barrier
	ds_read_b128 v[168:171], v147 offset:16384
	ds_read_b128 v[172:175], v147 offset:17408
	ds_read_b128 v[176:179], v147 offset:18432
	ds_read_b128 v[180:183], v147 offset:19456
	ds_read_b128 v[184:187], v147 offset:20480
	ds_read_b128 v[188:191], v147 offset:21504
	ds_read_b128 v[192:195], v147 offset:22528
	ds_read_b128 v[198:201], v147 offset:23552
	global_load_lds_dwordx4 v[222:223], off
	v_lshl_add_u64 v[224:225], s[52:53], 0, v[130:131]
	s_mov_b32 m0, s54
	s_nop 0
	global_load_lds_dwordx4 v[224:225], off
	s_barrier
	s_waitcnt lgkmcnt(0)
	s_setprio 1
	s_waitcnt lgkmcnt(0)
	v_mfma_f32_16x16x32_bf16 v[62:65], v[140:143], v[168:171], v[62:65]
	v_mfma_f32_16x16x32_bf16 v[58:61], v[154:157], v[168:171], v[58:61]
	v_mfma_f32_16x16x32_bf16 v[46:49], v[140:143], v[176:179], v[46:49]
	v_mfma_f32_16x16x32_bf16 v[42:45], v[154:157], v[176:179], v[42:45]
	v_mfma_f32_16x16x32_bf16 v[30:33], v[140:143], v[184:187], v[30:33]
	v_mfma_f32_16x16x32_bf16 v[26:29], v[154:157], v[184:187], v[26:29]
	v_mfma_f32_16x16x32_bf16 v[14:17], v[140:143], v[192:195], v[14:17]
	v_mfma_f32_16x16x32_bf16 v[10:13], v[154:157], v[192:195], v[10:13]
	v_mfma_f32_16x16x32_bf16 v[62:65], v[150:153], v[172:175], v[62:65]
	v_mfma_f32_16x16x32_bf16 v[58:61], v[158:161], v[172:175], v[58:61]
	v_mfma_f32_16x16x32_bf16 v[46:49], v[150:153], v[180:183], v[46:49]
	v_mfma_f32_16x16x32_bf16 v[42:45], v[158:161], v[180:183], v[42:45]
	v_mfma_f32_16x16x32_bf16 v[30:33], v[150:153], v[188:191], v[30:33]
	v_mfma_f32_16x16x32_bf16 v[26:29], v[158:161], v[188:191], v[26:29]
	v_mfma_f32_16x16x32_bf16 v[14:17], v[150:153], v[198:201], v[14:17]
	v_mfma_f32_16x16x32_bf16 v[10:13], v[158:161], v[198:201], v[10:13]
	s_setprio 0
	s_barrier
; #define PG8_STAGE(bufoff, gbase, voff) do { _Pragma("unroll") for (int _i = 0; _i < 2; ++_i) \
;         __builtin_amdgcn_global_load_lds((const unsigned*)((const char*)(gbase) + (voff)[_i]), (LAS unsigned*)(lds + (bufoff) + ldsw + _i * 8192), 16, 0, 0); } while (0)
; #define PG8_LDA(dst, b, h) do { _Pragma("unroll") for (int m = 0; m < 4; ++m) _Pragma("unroll") for (int k = 0; k < 2; ++k) dst[m][k] = *(const LAS bf16x8*)(lds + PG8_SA(b, h) + aoff + m * 2048 + k * 1024); } while (0)
; #define PG8_LDB(dst, b, h) do { _Pragma("unroll") for (int n = 0; n < 2; ++n) _Pragma("unroll") for (int k = 0; k < 2; ++k) dst[n][k] = *(const LAS bf16x8*)(lds + PG8_SB(b, h) + boff + n * 2048 + k * 1024); } while (0)
; #define PG8_MMA(ai, bj, At, Bt) do { __builtin_amdgcn_s_setprio(1); _Pragma("unroll") for (int m = 0; m < 4; ++m) _Pragma("unroll") for (int n = 0; n < 2; ++n) _Pragma("unroll") for (int k = 0; k < 2; ++k) \
;         acc[ai][bj][m][n] = __builtin_amdgcn_mfma_f32_16x16x32_bf16(Bt[n][k], At[m][k], acc[ai][bj][m][n], 0, 0, 0); __builtin_amdgcn_s_setprio(0); } while (0)
; #define PG8_WAIT_V(n) asm volatile("s_waitcnt vmcnt(" #n ")" ::: "memory")
; #define PG8_WAIT_L(n) asm volatile("s_waitcnt lgkmcnt(" #n ")" ::: "memory")
; #define PG8_BAR __builtin_amdgcn_s_barrier()
; #define PG8_SCHED __builtin_amdgcn_sched_barrier(0)
; template <class Epi, class Sched>
; DI void gemm_phase(LAS unsigned char* lds, const Gemm g, const Sched& S, const Epi& E) {
;     ...
;             PG8_BAR; PG8_WAIT_L(0); PG8_MMA(1, 0, At, B0); PG8_BAR; PG8_SCHED;
;             PG8_STAGE(PG8_SB(0, 1), b2 + hstep, voffB);
;             PG8_WAIT_V(6); PG8_BAR; PG8_MMA(1, 1, At, B1); PG8_BAR;
;             PG8_LDB(B0, 1, 0); PG8_SCHED; PG8_LDA(At, 1, 0); PG8_STAGE(PG8_SA(0, 1), a2 + hstep, voffA);
;             PG8_WAIT_L(8); PG8_BAR; PG8_WAIT_L(0); PG8_MMA(0, 0, At, B0); PG8_BAR; PG8_SCHED;
;             PG8_LDB(B1, 1, 1); PG8_STAGE(PG8_SB(1, 0), b3, voffB);
;             PG8_BAR; PG8_WAIT_L(0); PG8_MMA(0, 1, At, B1); PG8_BAR;
	s_add_u32 s88, s50, 0x80000
	s_addc_u32 s89, s51, 0
	s_add_i32 s83, s64, s33
	v_lshl_add_u64 v[140:141], s[88:89], 0, v[132:133]
	s_mov_b32 m0, s83
	s_nop 0
	global_load_lds_dwordx4 v[140:141], off
	v_lshl_add_u64 v[140:141], s[88:89], 0, v[130:131]
	s_add_i32 m0, s83, 0x2000
	s_nop 0
	global_load_lds_dwordx4 v[140:141], off
	s_waitcnt vmcnt(6)
	s_barrier
	s_setprio 1
	v_mfma_f32_16x16x32_bf16 v[54:57], v[202:205], v[168:171], v[54:57]
	v_mfma_f32_16x16x32_bf16 v[50:53], v[210:213], v[168:171], v[50:53]
	v_mfma_f32_16x16x32_bf16 v[38:41], v[202:205], v[176:179], v[38:41]
	v_mfma_f32_16x16x32_bf16 v[34:37], v[210:213], v[176:179], v[34:37]
	v_mfma_f32_16x16x32_bf16 v[22:25], v[202:205], v[184:187], v[22:25]
	v_mfma_f32_16x16x32_bf16 v[18:21], v[210:213], v[184:187], v[18:21]
	v_mfma_f32_16x16x32_bf16 v[6:9], v[202:205], v[192:195], v[6:9]
	v_mfma_f32_16x16x32_bf16 v[2:5], v[210:213], v[192:195], v[2:5]
	v_mfma_f32_16x16x32_bf16 v[54:57], v[206:209], v[172:175], v[54:57]
	v_mfma_f32_16x16x32_bf16 v[50:53], v[214:217], v[172:175], v[50:53]
	v_mfma_f32_16x16x32_bf16 v[38:41], v[206:209], v[180:183], v[38:41]
	v_mfma_f32_16x16x32_bf16 v[34:37], v[214:217], v[180:183], v[34:37]
	v_mfma_f32_16x16x32_bf16 v[22:25], v[206:209], v[188:191], v[22:25]
	v_mfma_f32_16x16x32_bf16 v[18:21], v[214:217], v[188:191], v[18:21]
	v_mfma_f32_16x16x32_bf16 v[6:9], v[206:209], v[198:201], v[6:9]
	v_mfma_f32_16x16x32_bf16 v[2:5], v[214:217], v[198:201], v[2:5]
	s_setprio 0
	s_add_i32 s83, 0, 0x18000
	v_add_u32_e32 v134, s83, v145
	s_barrier
	ds_read_b128 v[140:143], v134
	ds_read_b128 v[150:153], v134 offset:1024
	ds_read_b128 v[154:157], v134 offset:2048
	ds_read_b128 v[158:161], v134 offset:3072
	s_add_u32 s52, s52, 0x80000
	s_addc_u32 s53, s53, 0
	s_mov_b32 m0, s55
	v_lshl_add_u64 v[202:203], s[52:53], 0, v[132:133]
	ds_read_b128 v[168:171], v147 offset:32768
	ds_read_b128 v[172:175], v147 offset:33792
	ds_read_b128 v[176:179], v147 offset:34816
	ds_read_b128 v[180:183], v147 offset:35840
	ds_read_b128 v[184:187], v147 offset:36864
	ds_read_b128 v[188:191], v147 offset:37888
	ds_read_b128 v[192:195], v147 offset:38912
	ds_read_b128 v[198:201], v147 offset:39936
	global_load_lds_dwordx4 v[202:203], off
	v_lshl_add_u64 v[202:203], s[52:53], 0, v[130:131]
	s_mov_b32 m0, s57
	s_nop 0
	global_load_lds_dwordx4 v[202:203], off
	s_waitcnt lgkmcnt(8)
	s_barrier
	s_waitcnt lgkmcnt(0)
	s_setprio 1
	s_waitcnt lgkmcnt(0)
	v_mfma_f32_16x16x32_bf16 v[126:129], v[140:143], v[168:171], v[126:129]
	v_mfma_f32_16x16x32_bf16 v[122:125], v[154:157], v[168:171], v[122:125]
	v_mfma_f32_16x16x32_bf16 v[110:113], v[140:143], v[176:179], v[110:113]
	v_mfma_f32_16x16x32_bf16 v[106:109], v[154:157], v[176:179], v[106:109]
	v_mfma_f32_16x16x32_bf16 v[94:97], v[140:143], v[184:187], v[94:97]
	v_mfma_f32_16x16x32_bf16 v[90:93], v[154:157], v[184:187], v[90:93]
	v_mfma_f32_16x16x32_bf16 v[78:81], v[140:143], v[192:195], v[78:81]
	v_mfma_f32_16x16x32_bf16 v[74:77], v[154:157], v[192:195], v[74:77]
	v_mfma_f32_16x16x32_bf16 v[126:129], v[150:153], v[172:175], v[126:129]
	v_mfma_f32_16x16x32_bf16 v[122:125], v[158:161], v[172:175], v[122:125]
	v_mfma_f32_16x16x32_bf16 v[110:113], v[150:153], v[180:183], v[110:113]
	v_mfma_f32_16x16x32_bf16 v[106:109], v[158:161], v[180:183], v[106:109]
	v_mfma_f32_16x16x32_bf16 v[94:97], v[150:153], v[188:191], v[94:97]
	v_mfma_f32_16x16x32_bf16 v[90:93], v[158:161], v[188:191], v[90:93]
	v_mfma_f32_16x16x32_bf16 v[78:81], v[150:153], v[198:201], v[78:81]
	v_mfma_f32_16x16x32_bf16 v[74:77], v[158:161], v[198:201], v[74:77]
	s_setprio 0
	s_barrier
	s_add_i32 s52, 0, 0x1c000
	s_add_i32 s53, s83, s33
	v_add_u32_e32 v134, s52, v145
	v_lshl_add_u64 v[218:219], v[218:219], 0, s[10:11]
	s_mov_b32 m0, s53
	ds_read_b128 v[202:205], v134
	ds_read_b128 v[206:209], v134 offset:1024
	ds_read_b128 v[210:213], v134 offset:2048
	ds_read_b128 v[214:217], v134 offset:3072
	global_load_lds_dwordx4 v[218:219], off
	v_lshl_add_u64 v[218:219], v[220:221], 0, s[10:11]
	s_add_i32 m0, s53, 0x2000
	s_nop 0
	global_load_lds_dwordx4 v[218:219], off
	s_barrier
	s_waitcnt lgkmcnt(0)
	s_setprio 1
	s_waitcnt lgkmcnt(0)
	v_mfma_f32_16x16x32_bf16 v[118:121], v[202:205], v[168:171], v[118:121]
	v_mfma_f32_16x16x32_bf16 v[114:117], v[210:213], v[168:171], v[114:117]
	v_mfma_f32_16x16x32_bf16 v[102:105], v[202:205], v[176:179], v[102:105]
	v_mfma_f32_16x16x32_bf16 v[98:101], v[210:213], v[176:179], v[98:101]
	v_mfma_f32_16x16x32_bf16 v[86:89], v[202:205], v[184:187], v[86:89]
	v_mfma_f32_16x16x32_bf16 v[82:85], v[210:213], v[184:187], v[82:85]
	v_mfma_f32_16x16x32_bf16 v[70:73], v[202:205], v[192:195], v[70:73]
	v_mfma_f32_16x16x32_bf16 v[66:69], v[210:213], v[192:195], v[66:69]
	v_mfma_f32_16x16x32_bf16 v[118:121], v[206:209], v[172:175], v[118:121]
	v_mfma_f32_16x16x32_bf16 v[114:117], v[214:217], v[172:175], v[114:117]
	v_mfma_f32_16x16x32_bf16 v[102:105], v[206:209], v[180:183], v[102:105]
	v_mfma_f32_16x16x32_bf16 v[98:101], v[214:217], v[180:183], v[98:101]
	v_mfma_f32_16x16x32_bf16 v[86:89], v[206:209], v[188:191], v[86:89]
	v_mfma_f32_16x16x32_bf16 v[82:85], v[214:217], v[188:191], v[82:85]
	v_mfma_f32_16x16x32_bf16 v[70:73], v[206:209], v[198:201], v[70:73]
	v_mfma_f32_16x16x32_bf16 v[66:69], v[214:217], v[198:201], v[66:69]
	s_setprio 0
	s_mov_b32 m0, s59
	v_lshl_add_u64 v[218:219], v[222:223], 0, s[10:11]
	s_barrier
	ds_read_b128 v[168:171], v147 offset:49152
	ds_read_b128 v[172:175], v147 offset:50176
	ds_read_b128 v[176:179], v147 offset:51200
	ds_read_b128 v[180:183], v147 offset:52224
	ds_read_b128 v[184:187], v147 offset:53248
	ds_read_b128 v[188:191], v147 offset:54272
	ds_read_b128 v[192:195], v147 offset:55296
	ds_read_b128 v[198:201], v147 offset:56320
	global_load_lds_dwordx4 v[218:219], off
	v_lshl_add_u64 v[218:219], v[224:225], 0, s[10:11]
	s_mov_b32 m0, s62
	s_nop 0
	global_load_lds_dwordx4 v[218:219], off
	s_barrier
; DI float bflo(unsigned u) { return __uint_as_float(u << 16); }
; DI float bfhi(unsigned u) { return __uint_as_float(u & 0xffff0000u); }
; #define PG8_STAGE(bufoff, gbase, voff) do { _Pragma("unroll") for (int _i = 0; _i < 2; ++_i) \
;         __builtin_amdgcn_global_load_lds((const unsigned*)((const char*)(gbase) + (voff)[_i]), (LAS unsigned*)(lds + (bufoff) + ldsw + _i * 8192), 16, 0, 0); } while (0)
; #define PG8_LDA(dst, b, h) do { _Pragma("unroll") for (int m = 0; m < 4; ++m) _Pragma("unroll") for (int k = 0; k < 2; ++k) dst[m][k] = *(const LAS bf16x8*)(lds + PG8_SA(b, h) + aoff + m * 2048 + k * 1024); } while (0)
; #define PG8_MMA(ai, bj, At, Bt) do { __builtin_amdgcn_s_setprio(1); _Pragma("unroll") for (int m = 0; m < 4; ++m) _Pragma("unroll") for (int n = 0; n < 2; ++n) _Pragma("unroll") for (int k = 0; k < 2; ++k) \
;         acc[ai][bj][m][n] = __builtin_amdgcn_mfma_f32_16x16x32_bf16(Bt[n][k], At[m][k], acc[ai][bj][m][n], 0, 0, 0); __builtin_amdgcn_s_setprio(0); } while (0)
; #define PG8_WAIT_V(n) asm volatile("s_waitcnt vmcnt(" #n ")" ::: "memory")
; #define PG8_BAR __builtin_amdgcn_s_barrier()
;     DI void operator()(const f32x4 (&acc)[2][2][4][2], const Unit& u, int wr, int wc, int fr, int fq) const {
;         const int row0 = u.pm * BM + wr * 64 + fr, col0 = u.pn * BM + wc * 32 + 4 * fq;
; #pragma unroll
;         for (int ai = 0; ai < 2; ++ai)
; #pragma unroll
;             for (int m = 0; m < 4; ++m) { const size_t o = (size_t)(row0 + ai * HALF + m * 16) * 1024 + col0;
; #pragma unroll
;                 for (int bj = 0; bj < 2; ++bj)
; #pragma unroll
;                     for (int n = 0; n < 2; ++n) { const size_t oo = o + bj * HALF + n * 16; f32x4 rv;
;                         if (RES_BF16) { const u32x2 t = *(const u32x2*)((const bf16_t*)res + oo); rv = (f32x4){bflo(t.x), bfhi(t.x), bflo(t.y), bfhi(t.y)}; }
; template <class Epi, class Sched>
; DI void gemm_phase(LAS unsigned char* lds, const Gemm g, const Sched& S, const Epi& E) {
;     ...
;             PG8_BAR; PG8_WAIT_L(0); PG8_MMA(0, 1, At, B1); PG8_BAR;
;             PG8_LDA(At, 1, 1); PG8_STAGE(PG8_SA(1, 0), a3, voffA);
;             PG8_BAR; PG8_WAIT_L(0); PG8_MMA(1, 0, At, B0); PG8_BAR; PG8_SCHED;
;             PG8_STAGE(PG8_SB(1, 1), b3 + hstep, voffB);
;             PG8_WAIT_V(6); PG8_BAR; PG8_MMA(1, 1, At, B1); PG8_BAR;
;         }
;         E(acc, cur, wr, wc, fr, fq);
	s_waitcnt lgkmcnt(0)
	s_setprio 1
	s_waitcnt lgkmcnt(0)
	v_mfma_f32_16x16x32_bf16 v[62:65], v[140:143], v[168:171], v[62:65]
	v_mfma_f32_16x16x32_bf16 v[58:61], v[154:157], v[168:171], v[58:61]
	v_mfma_f32_16x16x32_bf16 v[46:49], v[140:143], v[176:179], v[46:49]
	v_mfma_f32_16x16x32_bf16 v[42:45], v[154:157], v[176:179], v[42:45]
	v_mfma_f32_16x16x32_bf16 v[30:33], v[140:143], v[184:187], v[30:33]
	v_mfma_f32_16x16x32_bf16 v[26:29], v[154:157], v[184:187], v[26:29]
	v_mfma_f32_16x16x32_bf16 v[14:17], v[140:143], v[192:195], v[14:17]
	v_mfma_f32_16x16x32_bf16 v[10:13], v[154:157], v[192:195], v[10:13]
	v_mfma_f32_16x16x32_bf16 v[62:65], v[150:153], v[172:175], v[62:65]
	v_mfma_f32_16x16x32_bf16 v[58:61], v[158:161], v[172:175], v[58:61]
	v_mfma_f32_16x16x32_bf16 v[46:49], v[150:153], v[180:183], v[46:49]
	v_mfma_f32_16x16x32_bf16 v[42:45], v[158:161], v[180:183], v[42:45]
	v_mfma_f32_16x16x32_bf16 v[30:33], v[150:153], v[188:191], v[30:33]
	v_mfma_f32_16x16x32_bf16 v[26:29], v[158:161], v[188:191], v[26:29]
	v_mfma_f32_16x16x32_bf16 v[14:17], v[150:153], v[198:201], v[14:17]
	v_mfma_f32_16x16x32_bf16 v[10:13], v[158:161], v[198:201], v[10:13]
	s_setprio 0
	s_barrier
	s_add_u32 s50, s50, 0x80080
	s_addc_u32 s51, s51, 0
	s_add_i32 s52, s52, s33
	v_lshl_add_u64 v[140:141], s[50:51], 0, v[132:133]
	s_mov_b32 m0, s52
	s_nop 0
	global_load_lds_dwordx4 v[140:141], off
	v_lshl_add_u64 v[140:141], s[50:51], 0, v[130:131]
	s_add_i32 m0, s52, 0x2000
	s_nop 0
	global_load_lds_dwordx4 v[140:141], off
	s_waitcnt vmcnt(6)
	s_barrier
	s_setprio 1
	v_mfma_f32_16x16x32_bf16 v[54:57], v[202:205], v[168:171], v[54:57]
	v_mfma_f32_16x16x32_bf16 v[50:53], v[210:213], v[168:171], v[50:53]
	v_mfma_f32_16x16x32_bf16 v[38:41], v[202:205], v[176:179], v[38:41]
	v_mfma_f32_16x16x32_bf16 v[34:37], v[210:213], v[176:179], v[34:37]
	v_mfma_f32_16x16x32_bf16 v[22:25], v[202:205], v[184:187], v[22:25]
	v_mfma_f32_16x16x32_bf16 v[18:21], v[210:213], v[184:187], v[18:21]
	v_mfma_f32_16x16x32_bf16 v[6:9], v[202:205], v[192:195], v[6:9]
	v_mfma_f32_16x16x32_bf16 v[2:5], v[210:213], v[192:195], v[2:5]
	v_mfma_f32_16x16x32_bf16 v[54:57], v[206:209], v[172:175], v[54:57]
	v_mfma_f32_16x16x32_bf16 v[50:53], v[214:217], v[172:175], v[50:53]
	v_mfma_f32_16x16x32_bf16 v[38:41], v[206:209], v[180:183], v[38:41]
	v_mfma_f32_16x16x32_bf16 v[34:37], v[214:217], v[180:183], v[34:37]
	v_mfma_f32_16x16x32_bf16 v[22:25], v[206:209], v[188:191], v[22:25]
	v_mfma_f32_16x16x32_bf16 v[18:21], v[214:217], v[188:191], v[18:21]
	v_mfma_f32_16x16x32_bf16 v[6:9], v[206:209], v[198:201], v[6:9]
	v_mfma_f32_16x16x32_bf16 v[2:5], v[214:217], v[198:201], v[2:5]
	s_setprio 0
	s_add_i32 s73, s73, 2
	s_add_u32 s42, s42, 0x100
	s_addc_u32 s43, s43, 0
	s_add_u32 s71, s71, 0x100
	s_addc_u32 s72, s72, 0
	s_cmp_gt_u32 s73, 29
	s_barrier
	s_cbranch_scc0 .LBB0_1523
	v_lshl_add_u32 v236, s56, 8, v144
	v_lshl_or_b32 v237, s84, 9, v149
	v_lshl_or_b32 v236, v236, 11, v237
	s_and_b64 vcc, exec, s[40:41]
	s_mov_b32 s84, s65
	s_mov_b32 s56, s66
	v_mov_b32_e32 v228, v236
	v_add_u32_e32 v229, 0x8000, v236
	v_add_u32_e32 v230, 0x10000, v236
	v_add_u32_e32 v231, 0x18000, v236
	v_add_u32_e32 v232, 0x40000, v236
	v_add_u32_e32 v233, 0x48000, v236
	v_add_u32_e32 v234, 0x50000, v236
	v_add_u32_e32 v235, 0x58000, v236
	global_load_dwordx2 v[140:141], v228, s[48:49]
	global_load_dwordx2 v[142:143], v228, s[48:49] offset:32
	global_load_dwordx2 v[150:151], v228, s[48:49] offset:256
	global_load_dwordx2 v[152:153], v228, s[48:49] offset:288
	global_load_dwordx2 v[154:155], v229, s[48:49]
	global_load_dwordx2 v[156:157], v229, s[48:49] offset:32
	global_load_dwordx2 v[158:159], v229, s[48:49] offset:256
	global_load_dwordx2 v[160:161], v229, s[48:49] offset:288
	global_load_dwordx2 v[168:169], v230, s[48:49]
	global_load_dwordx2 v[170:171], v230, s[48:49] offset:32
	global_load_dwordx2 v[172:173], v230, s[48:49] offset:256
	global_load_dwordx2 v[174:175], v230, s[48:49] offset:288
	global_load_dwordx2 v[176:177], v231, s[48:49]
	global_load_dwordx2 v[178:179], v231, s[48:49] offset:32
	global_load_dwordx2 v[180:181], v231, s[48:49] offset:256
	global_load_dwordx2 v[182:183], v231, s[48:49] offset:288
	global_load_dwordx2 v[184:185], v232, s[48:49]
	global_load_dwordx2 v[186:187], v232, s[48:49] offset:32
	global_load_dwordx2 v[188:189], v232, s[48:49] offset:256
	global_load_dwordx2 v[190:191], v232, s[48:49] offset:288
	global_load_dwordx2 v[192:193], v233, s[48:49]
	global_load_dwordx2 v[194:195], v233, s[48:49] offset:32
	global_load_dwordx2 v[198:199], v233, s[48:49] offset:256
	global_load_dwordx2 v[200:201], v233, s[48:49] offset:288
	global_load_dwordx2 v[202:203], v234, s[48:49]
	global_load_dwordx2 v[204:205], v234, s[48:49] offset:32
	global_load_dwordx2 v[206:207], v234, s[48:49] offset:256
	global_load_dwordx2 v[208:209], v234, s[48:49] offset:288
	global_load_dwordx2 v[210:211], v235, s[48:49]
	global_load_dwordx2 v[212:213], v235, s[48:49] offset:32
	global_load_dwordx2 v[214:215], v235, s[48:49] offset:256
	global_load_dwordx2 v[216:217], v235, s[48:49] offset:288
	s_waitcnt vmcnt(28)
; DI unsigned pk_bf16(float a, float b) { f32x2 v = {a, b}; bf2_t r = __builtin_convertvector(v, bf2_t); return __builtin_bit_cast(unsigned, r); }
; DI float bflo(unsigned u) { return __uint_as_float(u << 16); }
; DI float bfhi(unsigned u) { return __uint_as_float(u & 0xffff0000u); }
;     DI void operator()(const f32x4 (&acc)[2][2][4][2], const Unit& u, int wr, int wc, int fr, int fq) const {
;     ...
;             for (int m = 0; m < 4; ++m) { const size_t o = (size_t)(row0 + ai * HALF + m * 16) * 1024 + col0;
; #pragma unroll
;                 for (int bj = 0; bj < 2; ++bj)
; #pragma unroll
;                     for (int n = 0; n < 2; ++n) { const size_t oo = o + bj * HALF + n * 16; f32x4 rv;
;                         if (RES_BF16) { const u32x2 t = *(const u32x2*)((const bf16_t*)res + oo); rv = (f32x4){bflo(t.x), bfhi(t.x), bflo(t.y), bfhi(t.y)}; }
;                         else rv = *(const f32x4*)((const float*)res + oo);
;                         const f32x4 v = acc[ai][bj][m][n] + rv; u32x2 w; w.x = pk_bf16(v.x, v.y); w.y = pk_bf16(v.z, v.w);
;                         *(u32x2*)(O + oo) = w; } }
	v_lshlrev_b32_e32 v226, 16, v141
	v_and_b32_e32 v227, 0xffff0000, v141
	v_and_b32_e32 v141, 0xffff0000, v140
	v_lshlrev_b32_e32 v140, 16, v140
	v_pk_add_f32 v[128:129], v[128:129], v[226:227]
	v_pk_add_f32 v[126:127], v[126:127], v[140:141]
	v_lshlrev_b32_e32 v240, 16, v143
	v_and_b32_e32 v241, 0xffff0000, v143
	v_and_b32_e32 v143, 0xffff0000, v142
	v_lshlrev_b32_e32 v142, 16, v142
	v_pk_add_f32 v[124:125], v[124:125], v[240:241]
	v_pk_add_f32 v[122:123], v[122:123], v[142:143]
	v_lshlrev_b32_e32 v226, 16, v151
	v_and_b32_e32 v227, 0xffff0000, v151
	v_and_b32_e32 v151, 0xffff0000, v150
	v_lshlrev_b32_e32 v150, 16, v150
	v_pk_add_f32 v[120:121], v[120:121], v[226:227]
	v_pk_add_f32 v[118:119], v[118:119], v[150:151]
	v_lshlrev_b32_e32 v240, 16, v153
	v_and_b32_e32 v241, 0xffff0000, v153
	v_and_b32_e32 v153, 0xffff0000, v152
	v_lshlrev_b32_e32 v152, 16, v152
	v_pk_add_f32 v[116:117], v[116:117], v[240:241]
	v_pk_add_f32 v[114:115], v[114:115], v[152:153]
	v_cvt_pk_bf16_f32 v126, v126, v127
	v_cvt_pk_bf16_f32 v127, v128, v129
	v_cvt_pk_bf16_f32 v122, v122, v123
	v_cvt_pk_bf16_f32 v123, v124, v125
	v_cvt_pk_bf16_f32 v118, v118, v119
	v_cvt_pk_bf16_f32 v119, v120, v121
	v_cvt_pk_bf16_f32 v114, v114, v115
	v_cvt_pk_bf16_f32 v115, v116, v117
	global_store_dwordx2 v228, v[126:127], s[8:9] nt
	global_store_dwordx2 v228, v[122:123], s[8:9] offset:32 nt
	global_store_dwordx2 v228, v[118:119], s[8:9] offset:256 nt
	global_store_dwordx2 v228, v[114:115], s[8:9] offset:288 nt
	s_waitcnt vmcnt(28)
	v_lshlrev_b32_e32 v226, 16, v155
	v_and_b32_e32 v227, 0xffff0000, v155
	v_and_b32_e32 v155, 0xffff0000, v154
	v_lshlrev_b32_e32 v154, 16, v154
	v_pk_add_f32 v[112:113], v[112:113], v[226:227]
	v_pk_add_f32 v[110:111], v[110:111], v[154:155]
	v_lshlrev_b32_e32 v240, 16, v157
	v_and_b32_e32 v241, 0xffff0000, v157
	v_and_b32_e32 v157, 0xffff0000, v156
	v_lshlrev_b32_e32 v156, 16, v156
	v_pk_add_f32 v[108:109], v[108:109], v[240:241]
	v_pk_add_f32 v[106:107], v[106:107], v[156:157]
	v_lshlrev_b32_e32 v226, 16, v159
	v_and_b32_e32 v227, 0xffff0000, v159
	v_and_b32_e32 v159, 0xffff0000, v158
	v_lshlrev_b32_e32 v158, 16, v158
	v_pk_add_f32 v[104:105], v[104:105], v[226:227]
	v_pk_add_f32 v[102:103], v[102:103], v[158:159]
	v_lshlrev_b32_e32 v240, 16, v161
	v_and_b32_e32 v241, 0xffff0000, v161
	v_and_b32_e32 v161, 0xffff0000, v160
	v_lshlrev_b32_e32 v160, 16, v160
	v_pk_add_f32 v[100:101], v[100:101], v[240:241]
	v_pk_add_f32 v[98:99], v[98:99], v[160:161]
	v_cvt_pk_bf16_f32 v110, v110, v111
	v_cvt_pk_bf16_f32 v111, v112, v113
	v_cvt_pk_bf16_f32 v106, v106, v107
	v_cvt_pk_bf16_f32 v107, v108, v109
	v_cvt_pk_bf16_f32 v102, v102, v103
	v_cvt_pk_bf16_f32 v103, v104, v105
	v_cvt_pk_bf16_f32 v98, v98, v99
	v_cvt_pk_bf16_f32 v99, v100, v101
	global_store_dwordx2 v229, v[110:111], s[8:9] nt
	global_store_dwordx2 v229, v[106:107], s[8:9] offset:32 nt
	global_store_dwordx2 v229, v[102:103], s[8:9] offset:256 nt
	global_store_dwordx2 v229, v[98:99], s[8:9] offset:288 nt
	s_waitcnt vmcnt(28)
	v_lshlrev_b32_e32 v226, 16, v169
	v_and_b32_e32 v227, 0xffff0000, v169
	v_and_b32_e32 v169, 0xffff0000, v168
	v_lshlrev_b32_e32 v168, 16, v168
	v_pk_add_f32 v[96:97], v[96:97], v[226:227]
	v_pk_add_f32 v[94:95], v[94:95], v[168:169]
	v_lshlrev_b32_e32 v240, 16, v171
	v_and_b32_e32 v241, 0xffff0000, v171
	v_and_b32_e32 v171, 0xffff0000, v170
	v_lshlrev_b32_e32 v170, 16, v170
	v_pk_add_f32 v[92:93], v[92:93], v[240:241]
	v_pk_add_f32 v[90:91], v[90:91], v[170:171]
	v_lshlrev_b32_e32 v226, 16, v173
	v_and_b32_e32 v227, 0xffff0000, v173
	v_and_b32_e32 v173, 0xffff0000, v172
	v_lshlrev_b32_e32 v172, 16, v172
	v_pk_add_f32 v[88:89], v[88:89], v[226:227]
	v_pk_add_f32 v[86:87], v[86:87], v[172:173]
	v_lshlrev_b32_e32 v240, 16, v175
	v_and_b32_e32 v241, 0xffff0000, v175
	v_and_b32_e32 v175, 0xffff0000, v174
	v_lshlrev_b32_e32 v174, 16, v174
	v_pk_add_f32 v[84:85], v[84:85], v[240:241]
	v_pk_add_f32 v[82:83], v[82:83], v[174:175]
	v_cvt_pk_bf16_f32 v94, v94, v95
	v_cvt_pk_bf16_f32 v95, v96, v97
	v_cvt_pk_bf16_f32 v90, v90, v91
	v_cvt_pk_bf16_f32 v91, v92, v93
	v_cvt_pk_bf16_f32 v86, v86, v87
	v_cvt_pk_bf16_f32 v87, v88, v89
	v_cvt_pk_bf16_f32 v82, v82, v83
	v_cvt_pk_bf16_f32 v83, v84, v85
	global_store_dwordx2 v230, v[94:95], s[8:9] nt
	global_store_dwordx2 v230, v[90:91], s[8:9] offset:32 nt
	global_store_dwordx2 v230, v[86:87], s[8:9] offset:256 nt
	global_store_dwordx2 v230, v[82:83], s[8:9] offset:288 nt
	s_waitcnt vmcnt(28)
	v_lshlrev_b32_e32 v226, 16, v177
	v_and_b32_e32 v227, 0xffff0000, v177
	v_and_b32_e32 v177, 0xffff0000, v176
	v_lshlrev_b32_e32 v176, 16, v176
	v_pk_add_f32 v[80:81], v[80:81], v[226:227]
	v_pk_add_f32 v[78:79], v[78:79], v[176:177]
	v_lshlrev_b32_e32 v240, 16, v179
	v_and_b32_e32 v241, 0xffff0000, v179
	v_and_b32_e32 v179, 0xffff0000, v178
	v_lshlrev_b32_e32 v178, 16, v178
	v_pk_add_f32 v[76:77], v[76:77], v[240:241]
	v_pk_add_f32 v[74:75], v[74:75], v[178:179]
	v_lshlrev_b32_e32 v226, 16, v181
	v_and_b32_e32 v227, 0xffff0000, v181
	v_and_b32_e32 v181, 0xffff0000, v180
	v_lshlrev_b32_e32 v180, 16, v180
	v_pk_add_f32 v[72:73], v[72:73], v[226:227]
	v_pk_add_f32 v[70:71], v[70:71], v[180:181]
	v_lshlrev_b32_e32 v240, 16, v183
	v_and_b32_e32 v241, 0xffff0000, v183
	v_and_b32_e32 v183, 0xffff0000, v182
	v_lshlrev_b32_e32 v182, 16, v182
	v_pk_add_f32 v[68:69], v[68:69], v[240:241]
	v_pk_add_f32 v[66:67], v[66:67], v[182:183]
	v_cvt_pk_bf16_f32 v78, v78, v79
	v_cvt_pk_bf16_f32 v79, v80, v81
	v_cvt_pk_bf16_f32 v74, v74, v75
	v_cvt_pk_bf16_f32 v75, v76, v77
	v_cvt_pk_bf16_f32 v70, v70, v71
	v_cvt_pk_bf16_f32 v71, v72, v73
	v_cvt_pk_bf16_f32 v66, v66, v67
	v_cvt_pk_bf16_f32 v67, v68, v69
	global_store_dwordx2 v231, v[78:79], s[8:9] nt
	global_store_dwordx2 v231, v[74:75], s[8:9] offset:32 nt
	global_store_dwordx2 v231, v[70:71], s[8:9] offset:256 nt
	global_store_dwordx2 v231, v[66:67], s[8:9] offset:288 nt
	s_waitcnt vmcnt(28)
; DI unsigned pk_bf16(float a, float b) { f32x2 v = {a, b}; bf2_t r = __builtin_convertvector(v, bf2_t); return __builtin_bit_cast(unsigned, r); }
; DI float bflo(unsigned u) { return __uint_as_float(u << 16); }
; DI float bfhi(unsigned u) { return __uint_as_float(u & 0xffff0000u); }
; #define PG8_WAIT_V(n) asm volatile("s_waitcnt vmcnt(" #n ")" ::: "memory")
; #define PG8_BAR __builtin_amdgcn_s_barrier()
;     DI void operator()(const f32x4 (&acc)[2][2][4][2], const Unit& u, int wr, int wc, int fr, int fq) const {
;     ...
;             for (int m = 0; m < 4; ++m) { const size_t o = (size_t)(row0 + ai * HALF + m * 16) * 1024 + col0;
; #pragma unroll
;                 for (int bj = 0; bj < 2; ++bj)
; #pragma unroll
;                     for (int n = 0; n < 2; ++n) { const size_t oo = o + bj * HALF + n * 16; f32x4 rv;
;                         if (RES_BF16) { const u32x2 t = *(const u32x2*)((const bf16_t*)res + oo); rv = (f32x4){bflo(t.x), bfhi(t.x), bflo(t.y), bfhi(t.y)}; }
;                         else rv = *(const f32x4*)((const float*)res + oo);
;                         const f32x4 v = acc[ai][bj][m][n] + rv; u32x2 w; w.x = pk_bf16(v.x, v.y); w.y = pk_bf16(v.z, v.w);
;                         *(u32x2*)(O + oo) = w; } }
; template <class Epi, class Sched>
; DI void gemm_phase(LAS unsigned char* lds, const Gemm g, const Sched& S, const Epi& E) {
;     ...
;         if (!has_next) break;
; #pragma unroll
;         for (int a = 0; a < 2; ++a)
; #pragma unroll
;             for (int b = 0; b < 2; ++b)
; #pragma unroll
;                 for (int m = 0; m < 4; ++m)
; #pragma unroll
;                     for (int n = 0; n < 2; ++n) acc[a][b][m][n] = (f32x4){0.f, 0.f, 0.f, 0.f};
;         cur = nxt; cA = nA; cB = nB; ++ui;
;     }
;     PG8_WAIT_V(0);
;     if (wr == 0) PG8_BAR;
;     PG8_BAR;
	v_lshlrev_b32_e32 v226, 16, v185
	v_and_b32_e32 v227, 0xffff0000, v185
	v_and_b32_e32 v185, 0xffff0000, v184
	v_lshlrev_b32_e32 v184, 16, v184
	v_pk_add_f32 v[64:65], v[64:65], v[226:227]
	v_pk_add_f32 v[62:63], v[62:63], v[184:185]
	v_lshlrev_b32_e32 v240, 16, v187
	v_and_b32_e32 v241, 0xffff0000, v187
	v_and_b32_e32 v187, 0xffff0000, v186
	v_lshlrev_b32_e32 v186, 16, v186
	v_pk_add_f32 v[60:61], v[60:61], v[240:241]
	v_pk_add_f32 v[58:59], v[58:59], v[186:187]
	v_lshlrev_b32_e32 v226, 16, v189
	v_and_b32_e32 v227, 0xffff0000, v189
	v_and_b32_e32 v189, 0xffff0000, v188
	v_lshlrev_b32_e32 v188, 16, v188
	v_pk_add_f32 v[56:57], v[56:57], v[226:227]
	v_pk_add_f32 v[54:55], v[54:55], v[188:189]
	v_lshlrev_b32_e32 v240, 16, v191
	v_and_b32_e32 v241, 0xffff0000, v191
	v_and_b32_e32 v191, 0xffff0000, v190
	v_lshlrev_b32_e32 v190, 16, v190
	v_pk_add_f32 v[52:53], v[52:53], v[240:241]
	v_pk_add_f32 v[50:51], v[50:51], v[190:191]
	v_cvt_pk_bf16_f32 v62, v62, v63
	v_cvt_pk_bf16_f32 v63, v64, v65
	v_cvt_pk_bf16_f32 v58, v58, v59
	v_cvt_pk_bf16_f32 v59, v60, v61
	v_cvt_pk_bf16_f32 v54, v54, v55
	v_cvt_pk_bf16_f32 v55, v56, v57
	v_cvt_pk_bf16_f32 v50, v50, v51
	v_cvt_pk_bf16_f32 v51, v52, v53
	global_store_dwordx2 v232, v[62:63], s[8:9] nt
	global_store_dwordx2 v232, v[58:59], s[8:9] offset:32 nt
	global_store_dwordx2 v232, v[54:55], s[8:9] offset:256 nt
	global_store_dwordx2 v232, v[50:51], s[8:9] offset:288 nt
	s_waitcnt vmcnt(28)
	v_lshlrev_b32_e32 v226, 16, v193
	v_and_b32_e32 v227, 0xffff0000, v193
	v_and_b32_e32 v193, 0xffff0000, v192
	v_lshlrev_b32_e32 v192, 16, v192
	v_pk_add_f32 v[48:49], v[48:49], v[226:227]
	v_pk_add_f32 v[46:47], v[46:47], v[192:193]
	v_lshlrev_b32_e32 v240, 16, v195
	v_and_b32_e32 v241, 0xffff0000, v195
	v_and_b32_e32 v195, 0xffff0000, v194
	v_lshlrev_b32_e32 v194, 16, v194
	v_pk_add_f32 v[44:45], v[44:45], v[240:241]
	v_pk_add_f32 v[42:43], v[42:43], v[194:195]
	v_lshlrev_b32_e32 v226, 16, v199
	v_and_b32_e32 v227, 0xffff0000, v199
	v_and_b32_e32 v199, 0xffff0000, v198
	v_lshlrev_b32_e32 v198, 16, v198
	v_pk_add_f32 v[40:41], v[40:41], v[226:227]
	v_pk_add_f32 v[38:39], v[38:39], v[198:199]
	v_lshlrev_b32_e32 v240, 16, v201
	v_and_b32_e32 v241, 0xffff0000, v201
	v_and_b32_e32 v201, 0xffff0000, v200
	v_lshlrev_b32_e32 v200, 16, v200
	v_pk_add_f32 v[36:37], v[36:37], v[240:241]
	v_pk_add_f32 v[34:35], v[34:35], v[200:201]
	v_cvt_pk_bf16_f32 v46, v46, v47
	v_cvt_pk_bf16_f32 v47, v48, v49
	v_cvt_pk_bf16_f32 v42, v42, v43
	v_cvt_pk_bf16_f32 v43, v44, v45
	v_cvt_pk_bf16_f32 v38, v38, v39
	v_cvt_pk_bf16_f32 v39, v40, v41
	v_cvt_pk_bf16_f32 v34, v34, v35
	v_cvt_pk_bf16_f32 v35, v36, v37
	global_store_dwordx2 v233, v[46:47], s[8:9] nt
	global_store_dwordx2 v233, v[42:43], s[8:9] offset:32 nt
	global_store_dwordx2 v233, v[38:39], s[8:9] offset:256 nt
	global_store_dwordx2 v233, v[34:35], s[8:9] offset:288 nt
	s_waitcnt vmcnt(28)
	v_lshlrev_b32_e32 v226, 16, v203
	v_and_b32_e32 v227, 0xffff0000, v203
	v_and_b32_e32 v203, 0xffff0000, v202
	v_lshlrev_b32_e32 v202, 16, v202
	v_pk_add_f32 v[32:33], v[32:33], v[226:227]
	v_pk_add_f32 v[30:31], v[30:31], v[202:203]
	v_lshlrev_b32_e32 v240, 16, v205
	v_and_b32_e32 v241, 0xffff0000, v205
	v_and_b32_e32 v205, 0xffff0000, v204
	v_lshlrev_b32_e32 v204, 16, v204
	v_pk_add_f32 v[28:29], v[28:29], v[240:241]
	v_pk_add_f32 v[26:27], v[26:27], v[204:205]
	v_lshlrev_b32_e32 v226, 16, v207
	v_and_b32_e32 v227, 0xffff0000, v207
	v_and_b32_e32 v207, 0xffff0000, v206
	v_lshlrev_b32_e32 v206, 16, v206
	v_pk_add_f32 v[24:25], v[24:25], v[226:227]
	v_pk_add_f32 v[22:23], v[22:23], v[206:207]
	v_lshlrev_b32_e32 v240, 16, v209
	v_and_b32_e32 v241, 0xffff0000, v209
	v_and_b32_e32 v209, 0xffff0000, v208
	v_lshlrev_b32_e32 v208, 16, v208
	v_pk_add_f32 v[20:21], v[20:21], v[240:241]
	v_pk_add_f32 v[18:19], v[18:19], v[208:209]
	v_cvt_pk_bf16_f32 v30, v30, v31
	v_cvt_pk_bf16_f32 v31, v32, v33
	v_cvt_pk_bf16_f32 v26, v26, v27
	v_cvt_pk_bf16_f32 v27, v28, v29
	v_cvt_pk_bf16_f32 v22, v22, v23
	v_cvt_pk_bf16_f32 v23, v24, v25
	v_cvt_pk_bf16_f32 v18, v18, v19
	v_cvt_pk_bf16_f32 v19, v20, v21
	global_store_dwordx2 v234, v[30:31], s[8:9] nt
	global_store_dwordx2 v234, v[26:27], s[8:9] offset:32 nt
	global_store_dwordx2 v234, v[22:23], s[8:9] offset:256 nt
	global_store_dwordx2 v234, v[18:19], s[8:9] offset:288 nt
	s_waitcnt vmcnt(28)
	v_lshlrev_b32_e32 v226, 16, v211
	v_and_b32_e32 v227, 0xffff0000, v211
	v_and_b32_e32 v211, 0xffff0000, v210
	v_lshlrev_b32_e32 v210, 16, v210
	v_pk_add_f32 v[16:17], v[16:17], v[226:227]
	v_pk_add_f32 v[14:15], v[14:15], v[210:211]
	v_lshlrev_b32_e32 v240, 16, v213
	v_and_b32_e32 v241, 0xffff0000, v213
	v_and_b32_e32 v213, 0xffff0000, v212
	v_lshlrev_b32_e32 v212, 16, v212
	v_pk_add_f32 v[12:13], v[12:13], v[240:241]
	v_pk_add_f32 v[10:11], v[10:11], v[212:213]
	v_lshlrev_b32_e32 v226, 16, v215
	v_and_b32_e32 v227, 0xffff0000, v215
	v_and_b32_e32 v215, 0xffff0000, v214
	v_lshlrev_b32_e32 v214, 16, v214
	v_pk_add_f32 v[8:9], v[8:9], v[226:227]
	v_pk_add_f32 v[6:7], v[6:7], v[214:215]
	v_lshlrev_b32_e32 v240, 16, v217
	v_and_b32_e32 v241, 0xffff0000, v217
	v_and_b32_e32 v217, 0xffff0000, v216
	v_lshlrev_b32_e32 v216, 16, v216
	v_pk_add_f32 v[4:5], v[4:5], v[240:241]
	v_pk_add_f32 v[2:3], v[2:3], v[216:217]
	v_cvt_pk_bf16_f32 v14, v14, v15
	v_cvt_pk_bf16_f32 v15, v16, v17
	v_cvt_pk_bf16_f32 v10, v10, v11
	v_cvt_pk_bf16_f32 v11, v12, v13
	v_cvt_pk_bf16_f32 v6, v6, v7
	v_cvt_pk_bf16_f32 v7, v8, v9
	v_cvt_pk_bf16_f32 v2, v2, v3
	v_cvt_pk_bf16_f32 v3, v4, v5
	global_store_dwordx2 v235, v[14:15], s[8:9] nt
	global_store_dwordx2 v235, v[10:11], s[8:9] offset:32 nt
	global_store_dwordx2 v235, v[6:7], s[8:9] offset:256 nt
	global_store_dwordx2 v235, v[2:3], s[8:9] offset:288 nt
	s_cbranch_vccz .LBB0_1522
	s_waitcnt vmcnt(0)
	s_cmpk_gt_u32 s3, 0xff
	s_cbranch_scc1 .LBB0_1527
	s_barrier

; DI float bflo(unsigned u) { return __uint_as_float(u << 16); }
; DI float bfhi(unsigned u) { return __uint_as_float(u & 0xffff0000u); }
; DI void phase_final(const Params& p) {
;     ...
;     for (int tok = gw; tok < T_TOK; tok += nw) {
;         f32x4 v[4]; float ss = 0.f;
; #pragma unroll
;         for (int i = 0; i < 4; ++i) { const int c = 4 * lane + 256 * i;
;             if (tok < T_PR) { const u32x2 t = *(const u32x2*)(x2 + (size_t)tok * 1024 + c); v[i] = (f32x4){bflo(t.x), bfhi(t.x), bflo(t.y), bfhi(t.y)}; }
;             else { const size_t o = (size_t)(tok - T_PR) * 1024 + c; const u32x2 t = *(const u32x2*)(x1 + (size_t)tok * 1024 + c); v[i] = (f32x4){bflo(t.x), bfhi(t.x), bflo(t.y), bfhi(t.y)};
; #pragma unroll
;                 for (int s = 0; s < 8; ++s) v[i] += *(const f32x4*)((const float*)(p.ws + WS_PART2) + (size_t)s * 1048576 + o); }
;             ss += v[i].x * v[i].x + v[i].y * v[i].y + v[i].z * v[i].z + v[i].w * v[i].w; }
;         ss = wave_sum(ss);
;         const float rstd = rsqrtf(ss * (1.f / 1024.f) + 1e-6f);
; #pragma unroll
;         for (int i = 0; i < 4; ++i) { const f32x4 ww = *(const f32x4*)(p.fnorm_w + 4 * lane + 256 * i);
;             *(f32x4*)(p.out + O_Y + (size_t)tok * 1024 + 4 * lane + 256 * i) = (f32x4){v[i].x * rstd * ww.x, v[i].y * rstd * ww.y, v[i].z * rstd * ww.z, v[i].w * rstd * ww.w}; }
;     }
.Lfin_a_have:
	s_mov_b32 s7, 1
	v_lshlrev_b32_e32 v64, 16, v32
	v_and_b32_e32 v65, 0xffff0000, v32
	v_lshlrev_b32_e32 v66, 16, v33
	v_and_b32_e32 v67, 0xffff0000, v33
	v_lshlrev_b32_e32 v68, 16, v34
	v_and_b32_e32 v69, 0xffff0000, v34
	v_lshlrev_b32_e32 v70, 16, v35
	v_and_b32_e32 v71, 0xffff0000, v35
	v_lshlrev_b32_e32 v72, 16, v36
	v_and_b32_e32 v73, 0xffff0000, v36
	v_lshlrev_b32_e32 v74, 16, v37
	v_and_b32_e32 v75, 0xffff0000, v37
	v_lshlrev_b32_e32 v76, 16, v38
	v_and_b32_e32 v77, 0xffff0000, v38
	v_lshlrev_b32_e32 v78, 16, v39
	v_and_b32_e32 v79, 0xffff0000, v39
	v_mul_f32_e32 v48, v64, v64
	v_fmac_f32_e32 v48, v65, v65
	v_fmac_f32_e32 v48, v66, v66
	v_fmac_f32_e32 v48, v67, v67
	v_mul_f32_e32 v49, v68, v68
	v_fmac_f32_e32 v49, v69, v69
	v_fmac_f32_e32 v49, v70, v70
	v_fmac_f32_e32 v49, v71, v71
	v_mul_f32_e32 v50, v72, v72
	v_fmac_f32_e32 v50, v73, v73
	v_fmac_f32_e32 v50, v74, v74
	v_fmac_f32_e32 v50, v75, v75
	v_mul_f32_e32 v51, v76, v76
	v_fmac_f32_e32 v51, v77, v77
	v_fmac_f32_e32 v51, v78, v78
	v_fmac_f32_e32 v51, v79, v79
	v_add_f32_e32 v48, v48, v49
	v_add_f32_e32 v50, v50, v51
	v_add_f32_e32 v48, v48, v50
	s_nop 1
	v_add_f32_dpp v48, v48, v48 quad_perm:[1,0,3,2] row_mask:0xf bank_mask:0xf bound_ctrl:1
	s_nop 1
	v_add_f32_dpp v48, v48, v48 quad_perm:[2,3,0,1] row_mask:0xf bank_mask:0xf bound_ctrl:1
	s_nop 1
	v_add_f32_dpp v48, v48, v48 row_ror:4 row_mask:0xf bank_mask:0xf bound_ctrl:1
	s_nop 1
	v_add_f32_dpp v48, v48, v48 row_ror:8 row_mask:0xf bank_mask:0xf bound_ctrl:1
	s_nop 1
	v_readlane_b32 s16, v48, 0
	v_readlane_b32 s17, v48, 16
	v_readlane_b32 s18, v48, 32
	v_readlane_b32 s19, v48, 48
	s_nop 1
	v_mov_b32_e32 v52, s16
	v_add_f32_e32 v52, s17, v52
	v_add_f32_e32 v52, s18, v52
	v_add_f32_e32 v52, s19, v52
	v_fmamk_f32 v52, v52, 0x3a800000, v60
	v_rsq_f32_e32 v52, v52
	s_mov_b32 s11, 0
	s_lshl_b32 s10, s4, 12
	s_add_u32 s10, s76, s10
	s_addc_u32 s11, s77, 0
	v_mul_f32_e32 v64, v64, v52
	v_mul_f32_e32 v65, v65, v52
	v_mul_f32_e32 v66, v66, v52
	v_mul_f32_e32 v67, v67, v52
	v_mul_f32_e32 v64, v64, v16
	v_mul_f32_e32 v65, v65, v17
	v_mul_f32_e32 v66, v66, v18
	v_mul_f32_e32 v67, v67, v19
	global_store_dwordx4 v2, v[64:67], s[10:11] nt
	v_mul_f32_e32 v68, v68, v52
	v_mul_f32_e32 v69, v69, v52
	v_mul_f32_e32 v70, v70, v52
	v_mul_f32_e32 v71, v71, v52
	v_mul_f32_e32 v68, v68, v20
	v_mul_f32_e32 v69, v69, v21
	v_mul_f32_e32 v70, v70, v22
	v_mul_f32_e32 v71, v71, v23
	global_store_dwordx4 v2, v[68:71], s[10:11] offset:1024 nt
	v_mul_f32_e32 v72, v72, v52
	v_mul_f32_e32 v73, v73, v52
	v_mul_f32_e32 v74, v74, v52
	v_mul_f32_e32 v75, v75, v52
	v_mul_f32_e32 v72, v72, v24
	v_mul_f32_e32 v73, v73, v25
	v_mul_f32_e32 v74, v74, v26
	v_mul_f32_e32 v75, v75, v27
	global_store_dwordx4 v2, v[72:75], s[10:11] offset:2048 nt
	v_mul_f32_e32 v76, v76, v52
	v_mul_f32_e32 v77, v77, v52
	v_mul_f32_e32 v78, v78, v52
	v_mul_f32_e32 v79, v79, v52
	v_mul_f32_e32 v76, v76, v28
	v_mul_f32_e32 v77, v77, v29
	v_mul_f32_e32 v78, v78, v30
	v_mul_f32_e32 v79, v79, v31
	global_store_dwordx4 v2, v[76:79], s[10:11] offset:3072 nt
	s_mov_b32 s4, s6
	s_cmp_lt_u32 s4, 0x4000
	s_cbranch_scc0 .Lfin_sample

; DI float bflo(unsigned u) { return __uint_as_float(u << 16); }
; DI float bfhi(unsigned u) { return __uint_as_float(u & 0xffff0000u); }
; DI void phase_final(const Params& p) {
;     ...
;     for (int tok = gw; tok < T_TOK; tok += nw) {
;         f32x4 v[4]; float ss = 0.f;
; #pragma unroll
;         for (int i = 0; i < 4; ++i) { const int c = 4 * lane + 256 * i;
;             if (tok < T_PR) { const u32x2 t = *(const u32x2*)(x2 + (size_t)tok * 1024 + c); v[i] = (f32x4){bflo(t.x), bfhi(t.x), bflo(t.y), bfhi(t.y)}; }
;             else { const size_t o = (size_t)(tok - T_PR) * 1024 + c; const u32x2 t = *(const u32x2*)(x1 + (size_t)tok * 1024 + c); v[i] = (f32x4){bflo(t.x), bfhi(t.x), bflo(t.y), bfhi(t.y)};
; #pragma unroll
;                 for (int s = 0; s < 8; ++s) v[i] += *(const f32x4*)((const float*)(p.ws + WS_PART2) + (size_t)s * 1048576 + o); }
;             ss += v[i].x * v[i].x + v[i].y * v[i].y + v[i].z * v[i].z + v[i].w * v[i].w; }
;         ss = wave_sum(ss);
;         const float rstd = rsqrtf(ss * (1.f / 1024.f) + 1e-6f);
; #pragma unroll
;         for (int i = 0; i < 4; ++i) { const f32x4 ww = *(const f32x4*)(p.fnorm_w + 4 * lane + 256 * i);
;             *(f32x4*)(p.out + O_Y + (size_t)tok * 1024 + 4 * lane + 256 * i) = (f32x4){v[i].x * rstd * ww.x, v[i].y * rstd * ww.y, v[i].z * rstd * ww.z, v[i].w * rstd * ww.w}; }
;     }
.Lfin_b_have:
	s_mov_b32 s7, 1
	v_lshlrev_b32_e32 v64, 16, v40
	v_and_b32_e32 v65, 0xffff0000, v40
	v_lshlrev_b32_e32 v66, 16, v41
	v_and_b32_e32 v67, 0xffff0000, v41
	v_lshlrev_b32_e32 v68, 16, v42
	v_and_b32_e32 v69, 0xffff0000, v42
	v_lshlrev_b32_e32 v70, 16, v43
	v_and_b32_e32 v71, 0xffff0000, v43
	v_lshlrev_b32_e32 v72, 16, v44
	v_and_b32_e32 v73, 0xffff0000, v44
	v_lshlrev_b32_e32 v74, 16, v45
	v_and_b32_e32 v75, 0xffff0000, v45
	v_lshlrev_b32_e32 v76, 16, v46
	v_and_b32_e32 v77, 0xffff0000, v46
	v_lshlrev_b32_e32 v78, 16, v47
	v_and_b32_e32 v79, 0xffff0000, v47
	v_mul_f32_e32 v48, v64, v64
	v_fmac_f32_e32 v48, v65, v65
	v_fmac_f32_e32 v48, v66, v66
	v_fmac_f32_e32 v48, v67, v67
	v_mul_f32_e32 v49, v68, v68
	v_fmac_f32_e32 v49, v69, v69
	v_fmac_f32_e32 v49, v70, v70
	v_fmac_f32_e32 v49, v71, v71
	v_mul_f32_e32 v50, v72, v72
	v_fmac_f32_e32 v50, v73, v73
	v_fmac_f32_e32 v50, v74, v74
	v_fmac_f32_e32 v50, v75, v75
	v_mul_f32_e32 v51, v76, v76
	v_fmac_f32_e32 v51, v77, v77
	v_fmac_f32_e32 v51, v78, v78
	v_fmac_f32_e32 v51, v79, v79
	v_add_f32_e32 v48, v48, v49
	v_add_f32_e32 v50, v50, v51
	v_add_f32_e32 v48, v48, v50
	s_nop 1
	v_add_f32_dpp v48, v48, v48 quad_perm:[1,0,3,2] row_mask:0xf bank_mask:0xf bound_ctrl:1
	s_nop 1
	v_add_f32_dpp v48, v48, v48 quad_perm:[2,3,0,1] row_mask:0xf bank_mask:0xf bound_ctrl:1
	s_nop 1
	v_add_f32_dpp v48, v48, v48 row_ror:4 row_mask:0xf bank_mask:0xf bound_ctrl:1
	s_nop 1
	v_add_f32_dpp v48, v48, v48 row_ror:8 row_mask:0xf bank_mask:0xf bound_ctrl:1
	s_nop 1
	v_readlane_b32 s16, v48, 0
	v_readlane_b32 s17, v48, 16
	v_readlane_b32 s18, v48, 32
	v_readlane_b32 s19, v48, 48
	s_nop 1
	v_mov_b32_e32 v52, s16
	v_add_f32_e32 v52, s17, v52
	v_add_f32_e32 v52, s18, v52
	v_add_f32_e32 v52, s19, v52
	v_fmamk_f32 v52, v52, 0x3a800000, v60
	v_rsq_f32_e32 v52, v52
	s_mov_b32 s11, 0
	s_lshl_b32 s10, s4, 12
	s_add_u32 s10, s76, s10
	s_addc_u32 s11, s77, 0
	v_mul_f32_e32 v64, v64, v52
	v_mul_f32_e32 v65, v65, v52
	v_mul_f32_e32 v66, v66, v52
	v_mul_f32_e32 v67, v67, v52
	v_mul_f32_e32 v64, v64, v16
	v_mul_f32_e32 v65, v65, v17
	v_mul_f32_e32 v66, v66, v18
	v_mul_f32_e32 v67, v67, v19
	global_store_dwordx4 v2, v[64:67], s[10:11] nt
	v_mul_f32_e32 v68, v68, v52
	v_mul_f32_e32 v69, v69, v52
	v_mul_f32_e32 v70, v70, v52
	v_mul_f32_e32 v71, v71, v52
	v_mul_f32_e32 v68, v68, v20
	v_mul_f32_e32 v69, v69, v21
	v_mul_f32_e32 v70, v70, v22
	v_mul_f32_e32 v71, v71, v23
	global_store_dwordx4 v2, v[68:71], s[10:11] offset:1024 nt
	v_mul_f32_e32 v72, v72, v52
	v_mul_f32_e32 v73, v73, v52
	v_mul_f32_e32 v74, v74, v52
	v_mul_f32_e32 v75, v75, v52
	v_mul_f32_e32 v72, v72, v24
	v_mul_f32_e32 v73, v73, v25
	v_mul_f32_e32 v74, v74, v26
	v_mul_f32_e32 v75, v75, v27
	global_store_dwordx4 v2, v[72:75], s[10:11] offset:2048 nt
	v_mul_f32_e32 v76, v76, v52
	v_mul_f32_e32 v77, v77, v52
	v_mul_f32_e32 v78, v78, v52
	v_mul_f32_e32 v79, v79, v52
	v_mul_f32_e32 v76, v76, v28
	v_mul_f32_e32 v77, v77, v29
	v_mul_f32_e32 v78, v78, v30
	v_mul_f32_e32 v79, v79, v31
	global_store_dwordx4 v2, v[76:79], s[10:11] offset:3072 nt
	s_mov_b32 s4, s6
	s_cmp_lt_u32 s4, 0x4000
	s_cbranch_scc1 .Lfin_a
.Lfin_sample:
	s_cmp_lt_u32 s4, 0x4400
	s_cbranch_scc0 .Lfin_done
	v_mov_b32_e32 v60, 0x358637bd
	s_add_u32 s8, s78, 0xc480000
	s_addc_u32 s9, s79, 0
	s_lshl_b32 s5, s4, 11
	v_add_u32_e32 v4, s5, v3
	global_load_dwordx2 v[32:33], v4, s[8:9]
	global_load_dwordx2 v[34:35], v4, s[8:9] offset:512
	global_load_dwordx2 v[36:37], v4, s[8:9] offset:1024
	global_load_dwordx2 v[38:39], v4, s[8:9] offset:1536
	s_sub_u32 s5, s4, 0x4000
	s_lshl_b32 s5, s5, 12
	s_add_u32 s12, s78, 0x14c80000
	s_addc_u32 s13, s79, 0
	s_add_u32 s12, s12, s5
	s_addc_u32 s13, s13, 0
	global_load_dwordx4 v[80:83], v2, s[12:13]
	global_load_dwordx4 v[84:87], v2, s[12:13] offset:1024
	global_load_dwordx4 v[88:91], v2, s[12:13] offset:2048
	global_load_dwordx4 v[92:95], v2, s[12:13] offset:3072
	s_add_u32 s12, s12, 0x400000
	s_addc_u32 s13, s13, 0
	global_load_dwordx4 v[96:99], v2, s[12:13]
	global_load_dwordx4 v[100:103], v2, s[12:13] offset:1024
	global_load_dwordx4 v[104:107], v2, s[12:13] offset:2048
	global_load_dwordx4 v[108:111], v2, s[12:13] offset:3072
	s_add_u32 s12, s12, 0x400000
	s_addc_u32 s13, s13, 0
	global_load_dwordx4 v[112:115], v2, s[12:13]
	global_load_dwordx4 v[116:119], v2, s[12:13] offset:1024
	global_load_dwordx4 v[120:123], v2, s[12:13] offset:2048
	global_load_dwordx4 v[124:127], v2, s[12:13] offset:3072
	s_add_u32 s12, s12, 0x400000
	s_addc_u32 s13, s13, 0
	global_load_dwordx4 v[128:131], v2, s[12:13]
	global_load_dwordx4 v[132:135], v2, s[12:13] offset:1024
	global_load_dwordx4 v[136:139], v2, s[12:13] offset:2048
	global_load_dwordx4 v[140:143], v2, s[12:13] offset:3072
	s_add_u32 s12, s12, 0x400000
	s_addc_u32 s13, s13, 0
	global_load_dwordx4 v[144:147], v2, s[12:13]
	global_load_dwordx4 v[148:151], v2, s[12:13] offset:1024
	global_load_dwordx4 v[152:155], v2, s[12:13] offset:2048
	global_load_dwordx4 v[156:159], v2, s[12:13] offset:3072
	s_add_u32 s12, s12, 0x400000
	s_addc_u32 s13, s13, 0
	global_load_dwordx4 v[160:163], v2, s[12:13]
	global_load_dwordx4 v[164:167], v2, s[12:13] offset:1024
	global_load_dwordx4 v[168:171], v2, s[12:13] offset:2048
	global_load_dwordx4 v[172:175], v2, s[12:13] offset:3072
	s_add_u32 s12, s12, 0x400000
	s_addc_u32 s13, s13, 0
	global_load_dwordx4 v[176:179], v2, s[12:13]
	global_load_dwordx4 v[180:183], v2, s[12:13] offset:1024
	global_load_dwordx4 v[184:187], v2, s[12:13] offset:2048
	global_load_dwordx4 v[188:191], v2, s[12:13] offset:3072
	s_add_u32 s12, s12, 0x400000
	s_addc_u32 s13, s13, 0
	global_load_dwordx4 v[192:195], v2, s[12:13]
	global_load_dwordx4 v[196:199], v2, s[12:13] offset:1024
	global_load_dwordx4 v[200:203], v2, s[12:13] offset:2048
	global_load_dwordx4 v[204:207], v2, s[12:13] offset:3072
	s_waitcnt vmcnt(0)
; DI float bflo(unsigned u) { return __uint_as_float(u << 16); }
; DI float bfhi(unsigned u) { return __uint_as_float(u & 0xffff0000u); }
; DI void phase_final(const Params& p) {
;     ...
;             else { const size_t o = (size_t)(tok - T_PR) * 1024 + c; const u32x2 t = *(const u32x2*)(x1 + (size_t)tok * 1024 + c); v[i] = (f32x4){bflo(t.x), bfhi(t.x), bflo(t.y), bfhi(t.y)};
; #pragma unroll
;                 for (int s = 0; s < 8; ++s) v[i] += *(const f32x4*)((const float*)(p.ws + WS_PART2) + (size_t)s * 1048576 + o); }
;             ss += v[i].x * v[i].x + v[i].y * v[i].y + v[i].z * v[i].z + v[i].w * v[i].w; }
;         ss = wave_sum(ss);
;         const float rstd = rsqrtf(ss * (1.f / 1024.f) + 1e-6f);
; #pragma unroll
;         for (int i = 0; i < 4; ++i) { const f32x4 ww = *(const f32x4*)(p.fnorm_w + 4 * lane + 256 * i);
;             *(f32x4*)(p.out + O_Y + (size_t)tok * 1024 + 4 * lane + 256 * i) = (f32x4){v[i].x * rstd * ww.x, v[i].y * rstd * ww.y, v[i].z * rstd * ww.z, v[i].w * rstd * ww.w}; }
	v_lshlrev_b32_e32 v64, 16, v32
	v_and_b32_e32 v65, 0xffff0000, v32
	v_lshlrev_b32_e32 v66, 16, v33
	v_and_b32_e32 v67, 0xffff0000, v33
	v_lshlrev_b32_e32 v68, 16, v34
	v_and_b32_e32 v69, 0xffff0000, v34
	v_lshlrev_b32_e32 v70, 16, v35
	v_and_b32_e32 v71, 0xffff0000, v35
	v_lshlrev_b32_e32 v72, 16, v36
	v_and_b32_e32 v73, 0xffff0000, v36
	v_lshlrev_b32_e32 v74, 16, v37
	v_and_b32_e32 v75, 0xffff0000, v37
	v_lshlrev_b32_e32 v76, 16, v38
	v_and_b32_e32 v77, 0xffff0000, v38
	v_lshlrev_b32_e32 v78, 16, v39
	v_and_b32_e32 v79, 0xffff0000, v39
	v_add_f32_e32 v64, v64, v80
	v_add_f32_e32 v65, v65, v81
	v_add_f32_e32 v66, v66, v82
	v_add_f32_e32 v67, v67, v83
	v_add_f32_e32 v68, v68, v84
	v_add_f32_e32 v69, v69, v85
	v_add_f32_e32 v70, v70, v86
	v_add_f32_e32 v71, v71, v87
	v_add_f32_e32 v72, v72, v88
	v_add_f32_e32 v73, v73, v89
	v_add_f32_e32 v74, v74, v90
	v_add_f32_e32 v75, v75, v91
	v_add_f32_e32 v76, v76, v92
	v_add_f32_e32 v77, v77, v93
	v_add_f32_e32 v78, v78, v94
	v_add_f32_e32 v79, v79, v95
	v_add_f32_e32 v64, v64, v96
	v_add_f32_e32 v65, v65, v97
	v_add_f32_e32 v66, v66, v98
	v_add_f32_e32 v67, v67, v99
	v_add_f32_e32 v68, v68, v100
	v_add_f32_e32 v69, v69, v101
	v_add_f32_e32 v70, v70, v102
	v_add_f32_e32 v71, v71, v103
	v_add_f32_e32 v72, v72, v104
	v_add_f32_e32 v73, v73, v105
	v_add_f32_e32 v74, v74, v106
	v_add_f32_e32 v75, v75, v107
	v_add_f32_e32 v76, v76, v108
	v_add_f32_e32 v77, v77, v109
	v_add_f32_e32 v78, v78, v110
	v_add_f32_e32 v79, v79, v111
	v_add_f32_e32 v64, v64, v112
	v_add_f32_e32 v65, v65, v113
	v_add_f32_e32 v66, v66, v114
	v_add_f32_e32 v67, v67, v115
	v_add_f32_e32 v68, v68, v116
	v_add_f32_e32 v69, v69, v117
	v_add_f32_e32 v70, v70, v118
	v_add_f32_e32 v71, v71, v119
	v_add_f32_e32 v72, v72, v120
	v_add_f32_e32 v73, v73, v121
	v_add_f32_e32 v74, v74, v122
	v_add_f32_e32 v75, v75, v123
	v_add_f32_e32 v76, v76, v124
	v_add_f32_e32 v77, v77, v125
	v_add_f32_e32 v78, v78, v126
	v_add_f32_e32 v79, v79, v127
	v_add_f32_e32 v64, v64, v128
	v_add_f32_e32 v65, v65, v129
	v_add_f32_e32 v66, v66, v130
	v_add_f32_e32 v67, v67, v131
	v_add_f32_e32 v68, v68, v132
	v_add_f32_e32 v69, v69, v133
	v_add_f32_e32 v70, v70, v134
	v_add_f32_e32 v71, v71, v135
	v_add_f32_e32 v72, v72, v136
	v_add_f32_e32 v73, v73, v137
	v_add_f32_e32 v74, v74, v138
	v_add_f32_e32 v75, v75, v139
	v_add_f32_e32 v76, v76, v140
	v_add_f32_e32 v77, v77, v141
	v_add_f32_e32 v78, v78, v142
	v_add_f32_e32 v79, v79, v143
	v_add_f32_e32 v64, v64, v144
	v_add_f32_e32 v65, v65, v145
	v_add_f32_e32 v66, v66, v146
	v_add_f32_e32 v67, v67, v147
	v_add_f32_e32 v68, v68, v148
	v_add_f32_e32 v69, v69, v149
	v_add_f32_e32 v70, v70, v150
	v_add_f32_e32 v71, v71, v151
	v_add_f32_e32 v72, v72, v152
	v_add_f32_e32 v73, v73, v153
	v_add_f32_e32 v74, v74, v154
	v_add_f32_e32 v75, v75, v155
	v_add_f32_e32 v76, v76, v156
	v_add_f32_e32 v77, v77, v157
	v_add_f32_e32 v78, v78, v158
	v_add_f32_e32 v79, v79, v159
	v_add_f32_e32 v64, v64, v160
	v_add_f32_e32 v65, v65, v161
	v_add_f32_e32 v66, v66, v162
	v_add_f32_e32 v67, v67, v163
	v_add_f32_e32 v68, v68, v164
	v_add_f32_e32 v69, v69, v165
	v_add_f32_e32 v70, v70, v166
	v_add_f32_e32 v71, v71, v167
	v_add_f32_e32 v72, v72, v168
	v_add_f32_e32 v73, v73, v169
	v_add_f32_e32 v74, v74, v170
	v_add_f32_e32 v75, v75, v171
	v_add_f32_e32 v76, v76, v172
	v_add_f32_e32 v77, v77, v173
	v_add_f32_e32 v78, v78, v174
	v_add_f32_e32 v79, v79, v175
	v_add_f32_e32 v64, v64, v176
	v_add_f32_e32 v65, v65, v177
	v_add_f32_e32 v66, v66, v178
	v_add_f32_e32 v67, v67, v179
	v_add_f32_e32 v68, v68, v180
	v_add_f32_e32 v69, v69, v181
	v_add_f32_e32 v70, v70, v182
	v_add_f32_e32 v71, v71, v183
	v_add_f32_e32 v72, v72, v184
	v_add_f32_e32 v73, v73, v185
	v_add_f32_e32 v74, v74, v186
	v_add_f32_e32 v75, v75, v187
	v_add_f32_e32 v76, v76, v188
	v_add_f32_e32 v77, v77, v189
	v_add_f32_e32 v78, v78, v190
	v_add_f32_e32 v79, v79, v191
	v_add_f32_e32 v64, v64, v192
	v_add_f32_e32 v65, v65, v193
	v_add_f32_e32 v66, v66, v194
	v_add_f32_e32 v67, v67, v195
	v_add_f32_e32 v68, v68, v196
	v_add_f32_e32 v69, v69, v197
	v_add_f32_e32 v70, v70, v198
	v_add_f32_e32 v71, v71, v199
	v_add_f32_e32 v72, v72, v200
	v_add_f32_e32 v73, v73, v201
	v_add_f32_e32 v74, v74, v202
	v_add_f32_e32 v75, v75, v203
	v_add_f32_e32 v76, v76, v204
	v_add_f32_e32 v77, v77, v205
	v_add_f32_e32 v78, v78, v206
	v_add_f32_e32 v79, v79, v207
	v_mul_f32_e32 v48, v64, v64
	v_fmac_f32_e32 v48, v65, v65
	v_fmac_f32_e32 v48, v66, v66
	v_fmac_f32_e32 v48, v67, v67
	v_mul_f32_e32 v49, v68, v68
	v_fmac_f32_e32 v49, v69, v69
	v_fmac_f32_e32 v49, v70, v70
	v_fmac_f32_e32 v49, v71, v71
	v_mul_f32_e32 v50, v72, v72
	v_fmac_f32_e32 v50, v73, v73
	v_fmac_f32_e32 v50, v74, v74
	v_fmac_f32_e32 v50, v75, v75
	v_mul_f32_e32 v51, v76, v76
	v_fmac_f32_e32 v51, v77, v77
	v_fmac_f32_e32 v51, v78, v78
	v_fmac_f32_e32 v51, v79, v79
	v_add_f32_e32 v48, v48, v49
	v_add_f32_e32 v50, v50, v51
	v_add_f32_e32 v48, v48, v50
	s_nop 1
	v_add_f32_dpp v48, v48, v48 quad_perm:[1,0,3,2] row_mask:0xf bank_mask:0xf bound_ctrl:1
	s_nop 1
	v_add_f32_dpp v48, v48, v48 quad_perm:[2,3,0,1] row_mask:0xf bank_mask:0xf bound_ctrl:1
	s_nop 1
	v_add_f32_dpp v48, v48, v48 row_ror:4 row_mask:0xf bank_mask:0xf bound_ctrl:1
	s_nop 1
	v_add_f32_dpp v48, v48, v48 row_ror:8 row_mask:0xf bank_mask:0xf bound_ctrl:1
	s_nop 1
	v_readlane_b32 s16, v48, 0
	v_readlane_b32 s17, v48, 16
	v_readlane_b32 s18, v48, 32
	v_readlane_b32 s19, v48, 48
	s_nop 1
	v_mov_b32_e32 v52, s16
	v_add_f32_e32 v52, s17, v52
	v_add_f32_e32 v52, s18, v52
	v_add_f32_e32 v52, s19, v52
	v_fmamk_f32 v52, v52, 0x3a800000, v60
	v_rsq_f32_e32 v52, v52
	s_mov_b32 s11, 0
	s_lshl_b32 s10, s4, 12
	s_add_u32 s10, s76, s10
	s_addc_u32 s11, s77, 0
	v_mul_f32_e32 v64, v64, v52
	v_mul_f32_e32 v65, v65, v52
	v_mul_f32_e32 v66, v66, v52
	v_mul_f32_e32 v67, v67, v52
	v_mul_f32_e32 v64, v64, v16
	v_mul_f32_e32 v65, v65, v17
	v_mul_f32_e32 v66, v66, v18
	v_mul_f32_e32 v67, v67, v19
	global_store_dwordx4 v2, v[64:67], s[10:11] nt
	v_mul_f32_e32 v68, v68, v52
	v_mul_f32_e32 v69, v69, v52
	v_mul_f32_e32 v70, v70, v52
	v_mul_f32_e32 v71, v71, v52
	v_mul_f32_e32 v68, v68, v20
	v_mul_f32_e32 v69, v69, v21
	v_mul_f32_e32 v70, v70, v22
	v_mul_f32_e32 v71, v71, v23
	global_store_dwordx4 v2, v[68:71], s[10:11] offset:1024 nt
	v_mul_f32_e32 v72, v72, v52
	v_mul_f32_e32 v73, v73, v52
	v_mul_f32_e32 v74, v74, v52
	v_mul_f32_e32 v75, v75, v52
	v_mul_f32_e32 v72, v72, v24
	v_mul_f32_e32 v73, v73, v25
	v_mul_f32_e32 v74, v74, v26
	v_mul_f32_e32 v75, v75, v27
	global_store_dwordx4 v2, v[72:75], s[10:11] offset:2048 nt
	v_mul_f32_e32 v76, v76, v52
	v_mul_f32_e32 v77, v77, v52
	v_mul_f32_e32 v78, v78, v52
	v_mul_f32_e32 v79, v79, v52
	v_mul_f32_e32 v76, v76, v28
	v_mul_f32_e32 v77, v77, v29
	v_mul_f32_e32 v78, v78, v30
	v_mul_f32_e32 v79, v79, v31
	global_store_dwordx4 v2, v[76:79], s[10:11] offset:3072 nt
